# merge: next gate GEMM prologue DMA issued right after the branch GEMM end barrier, above the sigmoid/FMA epilogue (n=1,2)
# baseline (speedup 1.0000x reference)
; DI size_t wbase(int layer) { return (layer & 1) ? WS_W1 : WS_WINT; }
; DI void wait_vm0() { asm volatile("s_waitcnt vmcnt(0)" ::: "memory"); }
; DI int otid() { int t = threadIdx.x; asm volatile("" : "+v"(t)); return t; }
; template <int MB, bool SWAP>
; DI void gemm_kloop(f32x16 (&acc)[MB][2], const h16* __restrict__ A, int lda, const h16* __restrict__ B, int ldb, int K, char* lds) {
;     ...
;   const int tid = otid(), w = tid >> 6, lane = tid & 63;
;   const int wr = w >> 2, wc = w & 3;
;   const int lrow = w * 8 + (lane >> 3), pch = lane & 7;
;   const int gch = pch ^ ((lrow >> 1) & 7);
;   const unsigned voa = (unsigned)(lrow * lda + gch * 8) * 2u, vob = (unsigned)(lrow * ldb + gch * 8) * 2u;
;   const int lofs = lrow * 128 + pch * 16;
;   const int r32 = lane & 31, hh = lane >> 5, sw = (r32 >> 1) & 7;
;   const int a_rd = (wr * 32 * MB + r32) * 128;
;   const int b_rd = A_BYTES + (wc * 64 + r32) * 128;
;   const int nk = K >> 6;
;   constexpr int NP = MB + 4;
;   auto piece = [&](int p, int kt, int buf) {
;     char* s = lds + buf * STAGE;
;     if (p < MB) __builtin_amdgcn_global_load_lds((const unsigned*)((const char*)(A + (size_t)p * 64 * lda + kt * 64) + voa), (unsigned*)(s + p * 8192 + lofs), 16, 0, 0);
;     else __builtin_amdgcn_global_load_lds((const unsigned*)((const char*)(B + (size_t)(p - MB) * 64 * ldb + kt * 64) + vob), (unsigned*)(s + A_BYTES + (p - MB) * 8192 + lofs), 16, 0, 0);
;   };
;   wait_vm0();
; #pragma unroll
;   for (int p = 0; p < NP; ++p) piece(p, 0, 0);
; #pragma unroll
;   for (int p = 0; p < NP; ++p) piece(p, 1, 1);
; template <int MB>
; DI void merge_tile(const Params& P, int layer, size_t row0, int nt, char* smem) {
;   const h16* hb = (const h16*)(P.ws + WS_H16);
;   const h16* winT = (const h16*)(P.ws + wbase(layer));
;   const h16* wbrT = (const h16*)(P.ws + wbase(layer) + OFF_WBRT);
;   h16* mg = (h16*)(P.ws + WS_R1);
;   f32x16 macc[MB][2];
;   zero_acc<MB>(macc);
; #pragma unroll 1
;   for (int n = 0; n < 3; ++n) {
;     const h16* yn = (const h16*)(P.ws + (n == 0 ? WS_R2 : (n == 1 ? WS_YB : WS_YC)));
;     f32x16 pa2[MB][2];
;     half8 gpk[MB][2][2];
;     zero_acc<MB>(pa2);
;     gemm_kloop<MB, true>(pa2, hb + row0 * LDH, LDH, winT + (size_t)(G_OFF + n * 1024 + nt * 256) * LDH, LDH, D, smem);
.LBB0_37:
	s_add_i32 s2, s77, s25
	s_cmp_ge_i32 s2, s24
	s_cbranch_scc1 .LBB0_36
	s_bfe_u32 s3, s1, 0x20008
	s_and_b32 s24, s0, 7
	s_mul_i32 s25, s3, 0x48000
	s_add_u32 s40, s96, s25
	s_addc_u32 s41, s97, 0
	s_mul_i32 s3, s3, 0x88000
	s_add_u32 s42, s96, s3
	s_addc_u32 s43, s97, 0
	s_ashr_i32 s3, s2, 2
	s_and_b32 s25, s3, -8
	s_and_b32 s3, s2, 7
	s_or_b32 s46, s25, s3
	s_ashr_i32 s47, s46, 31
	s_mul_i32 s33, s46, 0x44000
	v_readlane_b32 s38, v255, 28
	s_mul_hi_i32 s3, s46, 0x44000
	v_readlane_b32 s39, v255, 29
	s_add_u32 s50, s38, s33
	s_addc_u32 s51, s39, s3
	s_lshl_b32 s2, s2, 5
	s_and_b32 s71, s2, 0x300
	s_add_i32 s74, s71, 0x1500
	s_add_u32 s86, s50, 0x22080
	v_readlane_b32 s52, v253, 1
	s_addc_u32 s87, s51, 0
	s_mul_i32 s3, s46, 0x24000
	v_readlane_b32 s66, v253, 15
	s_mul_hi_i32 s2, s46, 0x24000
	v_readlane_b32 s67, v253, 16
	s_add_u32 s3, s66, s3
	s_addc_u32 s2, s67, s2
	s_or_b32 s24, s25, s24
	s_mul_i32 s33, s24, 0x44000
	s_mul_hi_i32 s25, s24, 0x44000
	s_add_u32 s38, s66, s33
	s_addc_u32 s39, s67, s25
	s_mul_hi_i32 s25, s24, 0x24000
	s_mul_i32 s24, s24, 0x24000
	s_add_u32 s70, s66, s24
	v_mov_b32_e32 v197, 0
	s_addc_u32 s44, s67, s25
	s_mov_b32 s45, 0
	v_mov_b32_e32 v191, 0
	v_mov_b32_e32 v142, 0
	v_mov_b32_e32 v143, v197
	v_mov_b32_e32 v140, 0
	v_mov_b32_e32 v141, v197
	v_mov_b32_e32 v138, 0
	v_mov_b32_e32 v139, v197
	v_mov_b32_e32 v136, 0
	v_mov_b32_e32 v137, v197
	v_mov_b32_e32 v134, 0
	v_mov_b32_e32 v135, v197
	v_mov_b32_e32 v132, 0
	v_mov_b32_e32 v133, v197
	v_mov_b32_e32 v130, 0
	v_mov_b32_e32 v131, v197
	v_mov_b32_e32 v190, 0
	v_mov_b32_e32 v193, 0
	v_mov_b32_e32 v156, 0
	v_mov_b32_e32 v157, v197
	v_mov_b32_e32 v154, 0
	v_mov_b32_e32 v155, v197
	v_mov_b32_e32 v152, 0
	v_mov_b32_e32 v153, v197
	v_mov_b32_e32 v150, 0
	v_mov_b32_e32 v151, v197
	v_mov_b32_e32 v148, 0
	v_mov_b32_e32 v149, v197
	v_mov_b32_e32 v146, 0
	v_mov_b32_e32 v147, v197
	v_mov_b32_e32 v144, 0
	v_mov_b32_e32 v145, v197
	v_mov_b32_e32 v192, 0
	v_mov_b32_e32 v195, 0
	v_mov_b32_e32 v170, 0
	v_mov_b32_e32 v171, v197
	v_mov_b32_e32 v168, 0
	v_mov_b32_e32 v169, v197
	v_mov_b32_e32 v166, 0
	v_mov_b32_e32 v167, v197
	v_mov_b32_e32 v164, 0
	v_mov_b32_e32 v165, v197
	v_mov_b32_e32 v162, 0
	v_mov_b32_e32 v163, v197
	v_mov_b32_e32 v160, 0
	v_mov_b32_e32 v161, v197
	v_mov_b32_e32 v158, 0
	v_mov_b32_e32 v159, v197
	v_mov_b32_e32 v194, 0
	v_mov_b32_e32 v198, 0
	v_mov_b32_e32 v184, 0
	v_mov_b32_e32 v185, v197
	v_mov_b32_e32 v182, 0
	v_mov_b32_e32 v183, v197
	v_mov_b32_e32 v180, 0
	v_mov_b32_e32 v181, v197
	v_mov_b32_e32 v178, 0
	v_mov_b32_e32 v179, v197
	v_mov_b32_e32 v176, 0
	v_mov_b32_e32 v177, v197
	v_mov_b32_e32 v174, 0
	v_mov_b32_e32 v175, v197
	v_mov_b32_e32 v172, 0
	v_mov_b32_e32 v173, v197
	v_mov_b32_e32 v196, 0
	v_readlane_b32 s53, v253, 2
	v_readlane_b32 s54, v253, 3
	v_readlane_b32 s55, v253, 4
	v_readlane_b32 s56, v253, 5
	v_readlane_b32 s57, v253, 6
	v_readlane_b32 s58, v253, 7
	v_readlane_b32 s59, v253, 8
	v_readlane_b32 s60, v253, 9
	v_readlane_b32 s61, v253, 10
	v_readlane_b32 s62, v253, 11
	v_readlane_b32 s63, v253, 12
	v_readlane_b32 s64, v253, 13
	v_readlane_b32 s65, v253, 14
	s_branch .LBB0_39
.Lhead_pf:
	v_mov_b32_e32 v5, v208
	s_lshl_b32 vcc_lo, s45, 10
	v_ashrrev_i32_e32 v11, 3, v5
	v_bfe_u32 v12, v5, 3, 3
	v_and_or_b32 v0, v11, -8, v12
	v_lshrrev_b32_e32 v1, 1, v0
	v_xor_b32_e32 v1, v1, v5
	v_lshlrev_b32_e32 v1, 3, v1
	v_mul_lo_u32 v2, v0, s6
	v_and_b32_e32 v13, 56, v1
	v_or_b32_e32 v1, v13, v2
	v_lshlrev_b32_e32 v128, 1, v1
	v_lshlrev_b32_e32 v1, 4, v5
	v_and_b32_e32 v1, 0x70, v1
	v_lshl_or_b32 v8, v0, 7, v1
	v_add_u32_e32 v10, 0, v8
	v_add_u32_e32 v15, 0x2000, v10
	v_readfirstlane_b32 s33, v10
	s_add_i32 s24, s74, vcc_lo
	s_nop 0
	v_lshl_add_u64 v[2:3], s[50:51], 0, v[128:129]
	s_mov_b32 m0, s33
	s_mov_b64 s[52:53], 0x22000
	v_readfirstlane_b32 s33, v15
	s_mul_i32 s84, s24, 0x440
	v_lshl_add_u64 v[6:7], v[2:3], 0, s[52:53]
	s_mov_b32 m0, s33
	s_lshl_b64 s[24:25], s[84:85], 1
	v_add_u32_e32 v6, 0x4000, v10
	s_add_u32 s24, s96, s24
	v_and_b32_e32 v0, 31, v5
	v_lshrrev_b32_e32 v1, 2, v5
	v_readfirstlane_b32 s33, v6
	s_addc_u32 s25, s97, s25
	v_and_or_b32 v14, v1, s7, v0
	v_lshlrev_b32_e32 v0, 7, v5
	s_mov_b32 m0, s33
	v_add_u32_e32 v15, 0x6000, v10
	v_and_b32_e32 v4, 0x6f80, v0
	v_lshl_add_u64 v[0:1], s[24:25], 0, v[128:129]
	v_readfirstlane_b32 s24, v15
	v_lshl_add_u64 v[6:7], v[0:1], 0, s[52:53]
	s_mov_b32 m0, s24
	s_mov_b64 s[24:25], 0x44000
	v_add_u32_e32 v15, 0x8000, v10
	v_lshl_add_u64 v[6:7], v[0:1], 0, s[24:25]
	v_readfirstlane_b32 s24, v15
	s_mov_b32 m0, s24
	s_mov_b64 s[24:25], 0x66000
	v_add_u32_e32 v15, 0xa000, v10
	v_lshl_add_u64 v[6:7], v[0:1], 0, s[24:25]
	v_readfirstlane_b32 s24, v15
	s_mov_b32 m0, s24
	v_lshl_add_u64 v[2:3], v[2:3], 0, s[22:23]
	v_add_u32_e32 v7, 0xc000, v10
	v_lshrrev_b32_e32 v9, 1, v5
	v_readfirstlane_b32 s24, v7
	s_mov_b32 m0, s24
	v_add_u32_e32 v7, s8, v8
	v_add_u32_e32 v2, 0xe000, v10
	v_bfe_u32 v15, v5, 5, 1
	v_readfirstlane_b32 s24, v2
	s_mov_b32 m0, s24
	v_readfirstlane_b32 s24, v7
	v_lshl_add_u64 v[2:3], v[0:1], 0, s[22:23]
	s_mov_b32 m0, s24
	s_mov_b64 s[24:25], 0x22080
	v_add_u32_e32 v7, s9, v8
	v_lshl_add_u64 v[2:3], v[0:1], 0, s[24:25]
	v_readfirstlane_b32 s24, v7
	s_mov_b32 m0, s24
	s_mov_b64 s[24:25], 0x44080
	v_add_u32_e32 v7, s79, v8
	v_lshl_add_u64 v[2:3], v[0:1], 0, s[24:25]
	v_readfirstlane_b32 s24, v7
	s_mov_b32 m0, s24
	s_mov_b64 s[24:25], 0x66080
	v_add_u32_e32 v2, s10, v8
	v_lshl_add_u64 v[0:1], v[0:1], 0, s[24:25]
	v_readfirstlane_b32 s24, v2
	s_mov_b32 m0, s24
	v_lshlrev_b32_e32 v6, 7, v14
	s_branch .Lhead_cont

; template <int MB, bool SWAP>
; DI void gemm_kloop(f32x16 (&acc)[MB][2], const h16* __restrict__ A, int lda, const h16* __restrict__ B, int ldb, int K, char* lds) {
;     ...
;   const int lrow = w * 8 + (lane >> 3), pch = lane & 7;
;   const int gch = pch ^ ((lrow >> 1) & 7);
;   const unsigned voa = (unsigned)(lrow * lda + gch * 8) * 2u, vob = (unsigned)(lrow * ldb + gch * 8) * 2u;
;   const int lofs = lrow * 128 + pch * 16;
;   const int r32 = lane & 31, hh = lane >> 5, sw = (r32 >> 1) & 7;
;   const int a_rd = (wr * 32 * MB + r32) * 128;
;   const int b_rd = A_BYTES + (wc * 64 + r32) * 128;
;   const int nk = K >> 6;
;   constexpr int NP = MB + 4;
; template <int MB>
; DI void merge_tile(const Params& P, int layer, size_t row0, int nt, char* smem) {
;     ...
;     zero_acc<MB>(pa2);
;     gemm_kloop<MB, true>(pa2, hb + row0 * LDH, LDH, winT + (size_t)(G_OFF + n * 1024 + nt * 256) * LDH, LDH, D, smem);
.Lhead_cont:
	v_bfe_u32 v0, v5, 1, 3
	v_bitop3_b32 v1, v15, v9, 7 bitop3:0x78
	v_lshlrev_b32_e32 v9, 4, v1
	v_bitop3_b32 v1, v15, v0, 2 bitop3:0x36
	v_lshlrev_b32_e32 v8, 4, v1
	v_bitop3_b32 v1, v15, v0, 4 bitop3:0x36
	v_bitop3_b32 v0, v15, v0, 6 bitop3:0x36
	v_lshlrev_b32_e32 v5, 4, v0
	v_lshrrev_b32_e32 v0, 3, v11
	v_mul_lo_u32 v0, v0, s11
	v_mad_u32_u24 v0, v12, s6, v0
	v_or_b32_e32 v0, v0, v13
	v_lshlrev_b32_e32 v128, 1, v0
	v_lshlrev_b32_e32 v7, 4, v1
	v_lshl_add_u64 v[0:1], s[38:39], 0, v[128:129]
	v_lshl_add_u64 v[2:3], s[42:43], 0, v[128:129]
	s_mov_b64 s[80:81], 0
	s_mov_b32 s24, 0
	v_mov_b32_e32 v64, 0
	v_mov_b32_e32 v65, v197
	v_mov_b32_e32 v66, v197
	v_mov_b32_e32 v67, v197
	v_mov_b32_e32 v68, v197
	v_mov_b32_e32 v69, v197
	v_mov_b32_e32 v70, v197
	v_mov_b32_e32 v71, v197
	v_mov_b32_e32 v72, v197
	v_mov_b32_e32 v73, v197
	v_mov_b32_e32 v74, v197
	v_mov_b32_e32 v75, v197
	v_mov_b32_e32 v76, v197
	v_mov_b32_e32 v77, v197
	v_mov_b32_e32 v78, v197
	v_mov_b32_e32 v79, v197
	v_mov_b32_e32 v80, 0
	v_mov_b32_e32 v81, v197
	v_mov_b32_e32 v82, v197
	v_mov_b32_e32 v83, v197
	v_mov_b32_e32 v84, v197
	v_mov_b32_e32 v85, v197
	v_mov_b32_e32 v86, v197
	v_mov_b32_e32 v87, v197
	v_mov_b32_e32 v88, v197
	v_mov_b32_e32 v89, v197
	v_mov_b32_e32 v90, v197
	v_mov_b32_e32 v91, v197
	v_mov_b32_e32 v92, v197
	v_mov_b32_e32 v93, v197
	v_mov_b32_e32 v94, v197
	v_mov_b32_e32 v95, v197
	v_mov_b32_e32 v96, 0
	v_mov_b32_e32 v97, v197
	v_mov_b32_e32 v98, v197
	v_mov_b32_e32 v99, v197
	v_mov_b32_e32 v100, v197
	v_mov_b32_e32 v101, v197
	v_mov_b32_e32 v102, v197
	v_mov_b32_e32 v103, v197
	v_mov_b32_e32 v104, v197
	v_mov_b32_e32 v105, v197
	v_mov_b32_e32 v106, v197
	v_mov_b32_e32 v107, v197
	v_mov_b32_e32 v108, v197
	v_mov_b32_e32 v109, v197
	v_mov_b32_e32 v110, v197
	v_mov_b32_e32 v111, v197
	v_mov_b32_e32 v112, 0
	v_mov_b32_e32 v113, v197
	v_mov_b32_e32 v114, v197
	v_mov_b32_e32 v115, v197
	v_mov_b32_e32 v116, v197
	v_mov_b32_e32 v117, v197
	v_mov_b32_e32 v118, v197
	v_mov_b32_e32 v119, v197
	v_mov_b32_e32 v120, v197
	v_mov_b32_e32 v121, v197
	v_mov_b32_e32 v122, v197
	v_mov_b32_e32 v123, v197
	v_mov_b32_e32 v124, v197
	v_mov_b32_e32 v125, v197
	v_mov_b32_e32 v126, v197
	v_mov_b32_e32 v127, v197
	s_mov_b64 s[52:53], 0x3308100
	v_readfirstlane_b32 s25, v208
	s_nop 0
	s_lshr_b32 s25, s25, 8
	s_cmp_lg_u32 s25, 0
	s_cbranch_scc1 .Lstg40_top

; DI float sigmoid_f(float x) { return 1.f / (1.f + __expf(-x)); }
; template <int MB>
; DI void merge_tile(const Params& P, int layer, size_t row0, int nt, char* smem) {
;     ...
; #pragma unroll
;     for (int mb = 0; mb < MB; ++mb)
; #pragma unroll
;       for (int nb = 0; nb < 2; ++nb)
; #pragma unroll
;         for (int v = 0; v < 16; ++v) gpk[mb][nb][v >> 3][v & 7] = (h16)sigmoid_f(pa2[mb][nb][v]);
.Lstg42_join:
	v_mul_f32_e32 v112, 0xbfb8aa3b, v112
	v_exp_f32_e32 v237, v112
	v_mul_f32_e32 v113, 0xbfb8aa3b, v113
	v_mul_f32_e32 v120, 0xbfb8aa3b, v120
	v_mul_f32_e32 v127, 0xbfb8aa3b, v127
	v_mul_f32_e32 v128, 0xbfb8aa3b, v116
	v_mul_f32_e32 v187, 0xbfb8aa3b, v118
	v_exp_f32_e32 v118, v113
	v_exp_f32_e32 v113, v120
	v_exp_f32_e32 v120, v127
	v_add_f32_e32 v127, 1.0, v237
	v_mul_f32_e32 v114, 0xbfb8aa3b, v114
	v_mul_f32_e32 v186, 0xbfb8aa3b, v117
	v_exp_f32_e32 v117, v128
	v_div_scale_f32 v128, s[24:25], v127, v127, 1.0
	v_mul_f32_e32 v188, 0xbfb8aa3b, v119
	v_exp_f32_e32 v119, v114
	v_exp_f32_e32 v114, v186
	v_rcp_f32_e32 v186, v128
	v_mul_f32_e32 v115, 0xbfb8aa3b, v115
	v_exp_f32_e32 v116, v115
	v_exp_f32_e32 v115, v187
	v_fma_f32 v187, -v128, v186, 1.0
	v_fmac_f32_e32 v186, v187, v186
	v_div_scale_f32 v187, vcc, 1.0, v127, 1.0
	v_mul_f32_e32 v100, 0xbfb8aa3b, v100
	v_mul_f32_e32 v101, 0xbfb8aa3b, v101
	v_mul_f32_e32 v189, 0xbfb8aa3b, v102
	v_exp_f32_e32 v112, v188
	v_mul_f32_e32 v188, v187, v186
	v_mul_f32_e32 v205, 0xbfb8aa3b, v103
	v_exp_f32_e32 v103, v100
	v_exp_f32_e32 v100, v101
	v_exp_f32_e32 v101, v189
	v_fma_f32 v189, -v128, v188, v187
	v_fmac_f32_e32 v188, v189, v186
	v_fma_f32 v128, -v128, v188, v187
	v_add_f32_e32 v120, 1.0, v120
	v_div_fmas_f32 v128, v128, v186, v188
	v_div_fixup_f32 v127, v128, v127, 1.0
	v_div_scale_f32 v128, s[24:25], v120, v120, 1.0
	v_rcp_f32_e32 v186, v128
	v_mul_f32_e32 v121, 0xbfb8aa3b, v121
	v_mul_f32_e32 v96, 0xbfb8aa3b, v96
	v_mul_f32_e32 v215, 0xbfb8aa3b, v110
	v_fma_f32 v187, -v128, v186, 1.0
	v_fmac_f32_e32 v186, v187, v186
	v_div_scale_f32 v187, vcc, 1.0, v120, 1.0
	v_exp_f32_e32 v110, v121
	v_exp_f32_e32 v121, v96
	v_mul_f32_e32 v188, v187, v186
	v_fma_f32 v189, -v128, v188, v187
	v_fmac_f32_e32 v188, v189, v186
	v_fma_f32 v128, -v128, v188, v187
	v_add_f32_e32 v121, 1.0, v121
	v_div_fmas_f32 v128, v128, v186, v188
	v_div_fixup_f32 v120, v128, v120, 1.0
	v_div_scale_f32 v128, s[24:25], v121, v121, 1.0
	v_rcp_f32_e32 v186, v128
	v_mul_f32_e32 v122, 0xbfb8aa3b, v122
	v_mul_f32_e32 v216, 0xbfb8aa3b, v111
	v_exp_f32_e32 v111, v122
	v_fma_f32 v187, -v128, v186, 1.0
	v_fmac_f32_e32 v186, v187, v186
	v_div_scale_f32 v187, vcc, 1.0, v121, 1.0
	v_exp_f32_e32 v122, v216
	v_mul_f32_e32 v188, v187, v186
	v_fma_f32 v189, -v128, v188, v187
	v_fmac_f32_e32 v188, v189, v186
	v_fma_f32 v128, -v128, v188, v187
	v_add_f32_e32 v122, 1.0, v122
	v_div_fmas_f32 v128, v128, v186, v188
	v_div_fixup_f32 v121, v128, v121, 1.0
	v_div_scale_f32 v128, s[24:25], v122, v122, 1.0
	v_rcp_f32_e32 v186, v128
	v_mul_f32_e32 v123, 0xbfb8aa3b, v123
	v_mul_f32_e32 v80, 0xbfb8aa3b, v80
	v_mul_f32_e32 v212, 0xbfb8aa3b, v108
	v_fma_f32 v187, -v128, v186, 1.0
	v_fmac_f32_e32 v186, v187, v186
	v_div_scale_f32 v187, vcc, 1.0, v122, 1.0
	v_exp_f32_e32 v108, v123
	v_exp_f32_e32 v123, v80
	v_mul_f32_e32 v188, v187, v186
	v_fma_f32 v189, -v128, v188, v187
	v_fmac_f32_e32 v188, v189, v186
	v_fma_f32 v128, -v128, v188, v187
	v_add_f32_e32 v123, 1.0, v123
	v_div_fmas_f32 v128, v128, v186, v188
	v_div_fixup_f32 v122, v128, v122, 1.0
	v_div_scale_f32 v128, s[24:25], v123, v123, 1.0
	v_rcp_f32_e32 v186, v128
	v_mul_f32_e32 v124, 0xbfb8aa3b, v124
	v_mul_f32_e32 v228, 0xbfb8aa3b, v95
	v_mul_f32_e32 v213, 0xbfb8aa3b, v109
	v_fma_f32 v187, -v128, v186, 1.0
	v_fmac_f32_e32 v186, v187, v186
	v_div_scale_f32 v187, vcc, 1.0, v123, 1.0
	v_exp_f32_e32 v109, v124
	v_exp_f32_e32 v124, v228
	v_mul_f32_e32 v188, v187, v186
	v_fma_f32 v189, -v128, v188, v187
	v_fmac_f32_e32 v188, v189, v186
	v_fma_f32 v128, -v128, v188, v187
	v_add_f32_e32 v124, 1.0, v124
	v_div_fmas_f32 v128, v128, v186, v188
	v_div_fixup_f32 v128, v128, v123, 1.0
	v_div_scale_f32 v123, s[24:25], v124, v124, 1.0
	v_rcp_f32_e32 v186, v123
	v_mul_f32_e32 v125, 0xbfb8aa3b, v125
	v_mul_f32_e32 v64, 0xbfb8aa3b, v64
	v_mul_f32_e32 v210, 0xbfb8aa3b, v106
	v_fma_f32 v187, -v123, v186, 1.0
	v_fmac_f32_e32 v186, v187, v186
	v_div_scale_f32 v187, vcc, 1.0, v124, 1.0
	v_exp_f32_e32 v106, v125
	v_exp_f32_e32 v125, v64
	v_mul_f32_e32 v188, v187, v186
	v_fma_f32 v189, -v123, v188, v187
	v_fmac_f32_e32 v188, v189, v186
	v_fma_f32 v123, -v123, v188, v187
	v_add_f32_e32 v125, 1.0, v125
	v_div_fmas_f32 v123, v123, v186, v188
	v_div_fixup_f32 v186, v123, v124, 1.0
	v_div_scale_f32 v123, s[24:25], v125, v125, 1.0
	v_rcp_f32_e32 v124, v123
	v_mul_f32_e32 v126, 0xbfb8aa3b, v126
	v_mul_f32_e32 v236, 0xbfb8aa3b, v79
	v_mul_f32_e32 v211, 0xbfb8aa3b, v107
	v_fma_f32 v187, -v123, v124, 1.0
	v_fmac_f32_e32 v124, v187, v124
	v_div_scale_f32 v187, vcc, 1.0, v125, 1.0
	v_exp_f32_e32 v107, v126
	v_exp_f32_e32 v126, v236
	v_mul_f32_e32 v188, v187, v124
	v_fma_f32 v189, -v123, v188, v187
	v_fmac_f32_e32 v188, v189, v124
	v_fma_f32 v123, -v123, v188, v187
	v_add_f32_e32 v126, 1.0, v126
	v_div_fmas_f32 v123, v123, v124, v188
	v_div_fixup_f32 v187, v123, v125, 1.0
	v_div_scale_f32 v123, s[24:25], v126, v126, 1.0
	v_rcp_f32_e32 v124, v123
	v_mul_f32_e32 v217, 0xbfb8aa3b, v86
	v_add_u32_e32 v216, 0, v199
	v_mul_f32_e32 v97, 0xbfb8aa3b, v97
	v_fma_f32 v125, -v123, v124, 1.0
	v_fmac_f32_e32 v124, v125, v124
	v_div_scale_f32 v125, vcc, 1.0, v126, 1.0
	v_mul_f32_e32 v188, v125, v124
	v_fma_f32 v189, -v123, v188, v125
	v_fmac_f32_e32 v188, v189, v124
	v_fma_f32 v123, -v123, v188, v125
	v_div_fmas_f32 v123, v123, v124, v188
	v_cvt_f16_f32_e32 v124, v128
	v_add_u32_e32 v128, 0, v204
	v_mul_f32_e32 v98, 0xbfb8aa3b, v98
	v_mul_f32_e32 v99, 0xbfb8aa3b, v99
	v_mul_f32_e32 v206, 0xbfb8aa3b, v104
	v_mul_f32_e32 v207, 0xbfb8aa3b, v105
	v_mul_f32_e32 v81, 0xbfb8aa3b, v81
	v_mul_f32_e32 v84, 0xbfb8aa3b, v84
	v_mul_f32_e32 v218, 0xbfb8aa3b, v87
; DI float sigmoid_f(float x) { return 1.f / (1.f + __expf(-x)); }
; DI void wait_vm0() { asm volatile("s_waitcnt vmcnt(0)" ::: "memory"); }
; template <int MB, bool SWAP>
; DI void gemm_kloop(f32x16 (&acc)[MB][2], const h16* __restrict__ A, int lda, const h16* __restrict__ B, int ldb, int K, char* lds) {
;     ...
;   for (int kt = 0; kt < nk; ++kt) {
;     if (kt + 1 < nk) { if (MB == 2) asm volatile("s_waitcnt vmcnt(6)" ::: "memory"); else asm volatile("s_waitcnt vmcnt(5)" ::: "memory"); }
;     else wait_vm0();
;     __syncthreads();
;     const char* s = lds + cur * STAGE;
;     const int nbuf = cur == 0 ? 2 : cur - 1;
;     const bool more = kt + 2 < nk;
;     half8 af[2][MB], bf[2][2];
; #pragma unroll
;     for (int mb = 0; mb < MB; ++mb) af[0][mb] = *(const half8*)(s + a_rd + mb * 4096 + (((0 + hh) ^ sw) * 16));
; #pragma unroll
;     for (int nb = 0; nb < 2; ++nb) bf[0][nb] = *(const half8*)(s + b_rd + nb * 4096 + (((0 + hh) ^ sw) * 16));
; #pragma unroll
;     for (int ks = 0; ks < 4; ++ks) {
;       if (ks < 3) {
; #pragma unroll
;         for (int mb = 0; mb < MB; ++mb) af[(ks + 1) & 1][mb] = *(const half8*)(s + a_rd + mb * 4096 + (((2 * (ks + 1) + hh) ^ sw) * 16));
; #pragma unroll
;         for (int nb = 0; nb < 2; ++nb) bf[(ks + 1) & 1][nb] = *(const half8*)(s + b_rd + nb * 4096 + (((2 * (ks + 1) + hh) ^ sw) * 16));
;       }
;       if (more) {
;         if (2 * ks < NP) piece(2 * ks, kt + 2, nbuf);
;         if (2 * ks + 1 < NP) piece(2 * ks + 1, kt + 2, nbuf);
;       }
;       __builtin_amdgcn_sched_barrier(0);
;       __builtin_amdgcn_s_setprio(1);
; #pragma unroll
;       for (int mb = 0; mb < MB; ++mb)
; #pragma unroll
;         for (int nb = 0; nb < 2; ++nb)
;           acc[mb][nb] = SWAP ? __builtin_amdgcn_mfma_f32_32x32x16_f16(bf[ks & 1][nb], af[ks & 1][mb], acc[mb][nb], 0, 0, 0)
;                              : __builtin_amdgcn_mfma_f32_32x32x16_f16(af[ks & 1][mb], bf[ks & 1][nb], acc[mb][nb], 0, 0, 0);
;       __builtin_amdgcn_s_setprio(0);
;       __builtin_amdgcn_sched_barrier(0);
;     }
; template <int MB>
; DI void merge_tile(const Params& P, int layer, size_t row0, int nt, char* smem) {
;     ...
; #pragma unroll
;     for (int mb = 0; mb < MB; ++mb)
; #pragma unroll
;       for (int nb = 0; nb < 2; ++nb)
; #pragma unroll
;         for (int v = 0; v < 16; ++v) gpk[mb][nb][v >> 3][v & 7] = (h16)sigmoid_f(pa2[mb][nb][v]);
	v_mul_f32_e32 v224, 0xbfb8aa3b, v91
	v_mul_f32_e32 v225, 0xbfb8aa3b, v92
	v_mul_f32_e32 v226, 0xbfb8aa3b, v93
	v_mul_f32_e32 v227, 0xbfb8aa3b, v94
	v_exp_f32_e32 v93, v215
	v_exp_f32_e32 v87, v217
	v_div_fixup_f32 v188, v123, v126, 1.0
	v_add_u32_e32 v215, v128, v203
	v_add_u32_e32 v217, v216, v203
	v_mul_f32_e32 v221, 0xbfb8aa3b, v89
	v_mul_f32_e32 v223, 0xbfb8aa3b, v90
	v_mul_f32_e32 v65, 0xbfb8aa3b, v65
	v_mul_f32_e32 v66, 0xbfb8aa3b, v66
	v_mul_f32_e32 v67, 0xbfb8aa3b, v67
	v_mul_f32_e32 v68, 0xbfb8aa3b, v68
	v_mul_f32_e32 v69, 0xbfb8aa3b, v69
	v_mul_f32_e32 v70, 0xbfb8aa3b, v70
	v_mul_f32_e32 v71, 0xbfb8aa3b, v71
	v_mul_f32_e32 v229, 0xbfb8aa3b, v72
	v_mul_f32_e32 v230, 0xbfb8aa3b, v73
	v_mul_f32_e32 v231, 0xbfb8aa3b, v74
	v_mul_f32_e32 v232, 0xbfb8aa3b, v75
	v_mul_f32_e32 v233, 0xbfb8aa3b, v76
	v_mul_f32_e32 v234, 0xbfb8aa3b, v77
	v_mul_f32_e32 v235, 0xbfb8aa3b, v78
	v_exp_f32_e32 v104, v97
	v_exp_f32_e32 v105, v98
	v_exp_f32_e32 v102, v99
	v_exp_f32_e32 v98, v205
	v_exp_f32_e32 v99, v206
	v_exp_f32_e32 v96, v207
	v_exp_f32_e32 v97, v210
	v_exp_f32_e32 v94, v211
	v_exp_f32_e32 v95, v212
	v_exp_f32_e32 v92, v213
	v_exp_f32_e32 v90, v81
	v_exp_f32_e32 v89, v84
	v_exp_f32_e32 v84, v218
	v_exp_f32_e32 v80, v224
	v_exp_f32_e32 v81, v225
	v_exp_f32_e32 v78, v226
	v_exp_f32_e32 v79, v227
	v_cvt_f16_f32_e32 v125, v120
	v_cvt_f16_f32_e32 v126, v121
	v_cvt_f16_f32_e32 v123, v122
	v_cvt_f16_f32_e32 v121, v186
	v_cvt_f16_f32_e32 v122, v187
	v_cvt_f16_f32_e32 v120, v188
	s_waitcnt vmcnt(6)
	s_waitcnt lgkmcnt(0)
	s_barrier
	ds_read_b128 v[186:189], v215
	ds_read_b128 v[204:207], v215 offset:4096
	ds_read_b128 v[210:213], v217 offset:16384
	ds_read_b128 v[224:227], v217 offset:20480
	v_add_u32_e32 v217, v128, v202
	v_add_u32_e32 v218, v216, v202
	v_exp_f32_e32 v76, v65
	v_exp_f32_e32 v77, v66
	v_exp_f32_e32 v74, v67
	v_exp_f32_e32 v75, v68
	v_exp_f32_e32 v72, v69
	v_exp_f32_e32 v73, v70
	v_exp_f32_e32 v70, v71
	v_exp_f32_e32 v71, v229
	v_exp_f32_e32 v68, v230
	v_exp_f32_e32 v69, v231
	v_exp_f32_e32 v66, v232
	v_exp_f32_e32 v67, v233
	v_exp_f32_e32 v64, v234
	v_exp_f32_e32 v65, v235
	ds_read_b128 v[228:231], v217
	ds_read_b128 v[232:235], v217 offset:4096
	ds_read_b128 v[236:239], v218 offset:16384
	ds_read_b128 v[240:243], v218 offset:20480
	v_mul_f32_e32 v82, 0xbfb8aa3b, v82
	v_mul_f32_e32 v83, 0xbfb8aa3b, v83
	v_mul_f32_e32 v85, 0xbfb8aa3b, v85
	v_mul_f32_e32 v220, 0xbfb8aa3b, v88
	v_exp_f32_e32 v91, v82
	v_exp_f32_e32 v88, v83
	v_exp_f32_e32 v86, v85
	v_exp_f32_e32 v85, v220
	v_exp_f32_e32 v82, v221
	v_exp_f32_e32 v83, v223
	v_cvt_f16_f32_e32 v127, v127
	s_setprio 1
	s_waitcnt lgkmcnt(5)
	v_mfma_f32_32x32x16_f16 v[48:63], v[210:213], v[186:189], v[48:63]
	s_waitcnt lgkmcnt(4)
	v_mfma_f32_32x32x16_f16 v[32:47], v[224:227], v[186:189], v[32:47]
	v_mfma_f32_32x32x16_f16 v[16:31], v[210:213], v[204:207], v[16:31]
	v_mfma_f32_32x32x16_f16 v[0:15], v[224:227], v[204:207], v[0:15]
	s_setprio 0
	v_add_u32_e32 v218, v128, v201
	v_add_u32_e32 v220, v216, v201
	ds_read_b128 v[186:189], v218
	ds_read_b128 v[204:207], v218 offset:4096
	ds_read_b128 v[210:213], v220 offset:16384
	ds_read_b128 v[224:227], v220 offset:20480
	s_setprio 1
	s_waitcnt lgkmcnt(5)
	v_mfma_f32_32x32x16_f16 v[48:63], v[236:239], v[228:231], v[48:63]
	s_waitcnt lgkmcnt(4)
	v_mfma_f32_32x32x16_f16 v[32:47], v[240:243], v[228:231], v[32:47]
	v_mfma_f32_32x32x16_f16 v[16:31], v[236:239], v[232:235], v[16:31]
	v_mfma_f32_32x32x16_f16 v[0:15], v[240:243], v[232:235], v[0:15]
	s_setprio 0
	v_add_u32_e32 v128, v128, v200
	v_add_u32_e32 v216, v216, v200
	ds_read_b128 v[228:231], v128
	ds_read_b128 v[232:235], v128 offset:4096
	ds_read_b128 v[236:239], v216 offset:16384
	ds_read_b128 v[240:243], v216 offset:20480
	s_setprio 1
	s_waitcnt lgkmcnt(5)
	v_mfma_f32_32x32x16_f16 v[48:63], v[210:213], v[186:189], v[48:63]
	s_waitcnt lgkmcnt(4)
	v_mfma_f32_32x32x16_f16 v[32:47], v[224:227], v[186:189], v[32:47]
	v_mfma_f32_32x32x16_f16 v[16:31], v[210:213], v[204:207], v[16:31]
	v_mfma_f32_32x32x16_f16 v[0:15], v[224:227], v[204:207], v[0:15]
	s_setprio 0
	s_setprio 1
	s_waitcnt lgkmcnt(1)
	v_mfma_f32_32x32x16_f16 v[48:63], v[236:239], v[228:231], v[48:63]
	s_waitcnt lgkmcnt(0)
	v_mfma_f32_32x32x16_f16 v[32:47], v[240:243], v[228:231], v[32:47]
	v_mfma_f32_32x32x16_f16 v[16:31], v[236:239], v[232:235], v[16:31]
	v_mfma_f32_32x32x16_f16 v[0:15], v[240:243], v[232:235], v[0:15]
	s_setprio 0
	s_add_i32 s24, 0, 0xc000
	v_add3_u32 v203, s24, v203, v199
	s_waitcnt vmcnt(0)
	s_barrier
; DI void wait_vm0() { asm volatile("s_waitcnt vmcnt(0)" ::: "memory"); }
; template <int MB, bool SWAP>
; DI void gemm_kloop(f32x16 (&acc)[MB][2], const h16* __restrict__ A, int lda, const h16* __restrict__ B, int ldb, int K, char* lds) {
;     ...
;   for (int kt = 0; kt < nk; ++kt) {
;     if (kt + 1 < nk) { if (MB == 2) asm volatile("s_waitcnt vmcnt(6)" ::: "memory"); else asm volatile("s_waitcnt vmcnt(5)" ::: "memory"); }
;     else wait_vm0();
;     __syncthreads();
;     const char* s = lds + cur * STAGE;
;     const int nbuf = cur == 0 ? 2 : cur - 1;
;     const bool more = kt + 2 < nk;
;     half8 af[2][MB], bf[2][2];
; #pragma unroll
;     for (int mb = 0; mb < MB; ++mb) af[0][mb] = *(const half8*)(s + a_rd + mb * 4096 + (((0 + hh) ^ sw) * 16));
; #pragma unroll
;     for (int nb = 0; nb < 2; ++nb) bf[0][nb] = *(const half8*)(s + b_rd + nb * 4096 + (((0 + hh) ^ sw) * 16));
; #pragma unroll
;     for (int ks = 0; ks < 4; ++ks) {
;       if (ks < 3) {
; #pragma unroll
;         for (int mb = 0; mb < MB; ++mb) af[(ks + 1) & 1][mb] = *(const half8*)(s + a_rd + mb * 4096 + (((2 * (ks + 1) + hh) ^ sw) * 16));
; #pragma unroll
;         for (int nb = 0; nb < 2; ++nb) bf[(ks + 1) & 1][nb] = *(const half8*)(s + b_rd + nb * 4096 + (((2 * (ks + 1) + hh) ^ sw) * 16));
;       }
;       if (more) {
;         if (2 * ks < NP) piece(2 * ks, kt + 2, nbuf);
;         if (2 * ks + 1 < NP) piece(2 * ks + 1, kt + 2, nbuf);
;       }
;       __builtin_amdgcn_sched_barrier(0);
;       __builtin_amdgcn_s_setprio(1);
; #pragma unroll
;       for (int mb = 0; mb < MB; ++mb)
; #pragma unroll
;         for (int nb = 0; nb < 2; ++nb)
;           acc[mb][nb] = SWAP ? __builtin_amdgcn_mfma_f32_32x32x16_f16(bf[ks & 1][nb], af[ks & 1][mb], acc[mb][nb], 0, 0, 0)
;                              : __builtin_amdgcn_mfma_f32_32x32x16_f16(af[ks & 1][mb], bf[ks & 1][nb], acc[mb][nb], 0, 0, 0);
;       __builtin_amdgcn_s_setprio(0);
;       __builtin_amdgcn_sched_barrier(0);
;     }
;     cur = cur == 2 ? 0 : cur + 1;
;   }
;   __syncthreads();
; template <int MB>
; DI void merge_tile(const Params& P, int layer, size_t row0, int nt, char* smem) {
;     ...
; #pragma unroll
;     for (int mb = 0; mb < MB; ++mb)
; #pragma unroll
;       for (int nb = 0; nb < 2; ++nb)
; #pragma unroll
;         for (int v = 0; v < 16; ++v) macc[mb][nb][v] += (float)gpk[mb][nb][v >> 3][v & 7] * pa2[mb][nb][v];
	ds_read_b128 v[186:189], v215 offset:49152
	ds_read_b128 v[204:207], v215 offset:53248
	ds_read_b128 v[210:213], v203 offset:16384
	ds_read_b128 v[224:227], v203 offset:20480
	ds_read_b128 v[228:231], v217 offset:49152
	ds_read_b128 v[232:235], v217 offset:53248
	v_add3_u32 v202, s24, v202, v199
	ds_read_b128 v[236:239], v202 offset:16384
	ds_read_b128 v[240:243], v202 offset:20480
	s_setprio 1
	s_waitcnt lgkmcnt(5)
	v_mfma_f32_32x32x16_f16 v[48:63], v[210:213], v[186:189], v[48:63]
	s_waitcnt lgkmcnt(4)
	v_mfma_f32_32x32x16_f16 v[32:47], v[224:227], v[186:189], v[32:47]
	v_mfma_f32_32x32x16_f16 v[16:31], v[210:213], v[204:207], v[16:31]
	v_mfma_f32_32x32x16_f16 v[0:15], v[224:227], v[204:207], v[0:15]
	s_setprio 0
	v_add3_u32 v201, s24, v201, v199
	ds_read_b128 v[186:189], v218 offset:49152
	ds_read_b128 v[202:205], v218 offset:53248
	ds_read_b128 v[210:213], v201 offset:16384
	ds_read_b128 v[224:227], v201 offset:20480
	s_setprio 1
	s_waitcnt lgkmcnt(5)
	v_mfma_f32_32x32x16_f16 v[48:63], v[236:239], v[228:231], v[48:63]
	s_waitcnt lgkmcnt(4)
	v_mfma_f32_32x32x16_f16 v[32:47], v[240:243], v[228:231], v[32:47]
	v_mfma_f32_32x32x16_f16 v[16:31], v[236:239], v[232:235], v[16:31]
	v_mfma_f32_32x32x16_f16 v[0:15], v[240:243], v[232:235], v[0:15]
	s_setprio 0
	ds_read_b128 v[228:231], v128 offset:49152
	ds_read_b128 v[232:235], v128 offset:53248
	v_add3_u32 v128, s24, v200, v199
	ds_read_b128 v[236:239], v128 offset:16384
	ds_read_b128 v[240:243], v128 offset:20480
	s_setprio 1
	s_waitcnt lgkmcnt(5)
	v_mfma_f32_32x32x16_f16 v[48:63], v[210:213], v[186:189], v[48:63]
	s_waitcnt lgkmcnt(4)
	v_mfma_f32_32x32x16_f16 v[32:47], v[224:227], v[186:189], v[32:47]
	v_mfma_f32_32x32x16_f16 v[16:31], v[210:213], v[202:205], v[16:31]
	v_mfma_f32_32x32x16_f16 v[0:15], v[224:227], v[202:205], v[0:15]
	s_setprio 0
	s_setprio 1
	s_waitcnt lgkmcnt(1)
	v_mfma_f32_32x32x16_f16 v[48:63], v[236:239], v[228:231], v[48:63]
	s_waitcnt lgkmcnt(0)
	v_mfma_f32_32x32x16_f16 v[32:47], v[240:243], v[228:231], v[32:47]
	v_mfma_f32_32x32x16_f16 v[16:31], v[236:239], v[232:235], v[16:31]
	v_mfma_f32_32x32x16_f16 v[0:15], v[240:243], v[232:235], v[0:15]
	s_setprio 0
	v_add_f32_e64 v118, v118, 1.0
	v_add_f32_e64 v119, v119, 1.0
	s_nop 4
	v_fma_mix_f32 v198, v48, v127, v198 op_sel_hi:[0,1,0]
	v_div_scale_f32 v48, s[24:25], v119, v119, 1.0
	v_rcp_f32_e32 v127, v48
	v_fma_mix_f32 v195, v32, v126, v195 op_sel_hi:[0,1,0]
	v_fma_mix_f32 v193, v16, v124, v193 op_sel_hi:[0,1,0]
	v_fma_mix_f32 v191, v0, v122, v191 op_sel_hi:[0,1,0]
	v_fma_f32 v128, -v48, v127, 1.0
	v_fmac_f32_e32 v127, v128, v127
	v_div_scale_f32 v128, vcc, 1.0, v119, 1.0
	v_mul_f32_e32 v186, v128, v127
	v_fma_f32 v187, -v48, v186, v128
	v_fmac_f32_e32 v186, v187, v127
	v_fma_f32 v48, -v48, v186, v128
	v_div_fmas_f32 v48, v48, v127, v186
	v_div_fixup_f32 v48, v48, v119, 1.0
	v_div_scale_f32 v119, s[24:25], v118, v118, 1.0
	v_rcp_f32_e32 v127, v119
	s_add_i32 s45, s45, 1
	s_add_u32 s42, s42, 0x220000
	s_addc_u32 s43, s43, 0
	v_fma_f32 v128, -v119, v127, 1.0
	v_fmac_f32_e32 v127, v128, v127
	v_div_scale_f32 v128, vcc, 1.0, v118, 1.0
	v_mul_f32_e32 v186, v128, v127
	v_fma_f32 v187, -v119, v186, v128
	v_fmac_f32_e32 v186, v187, v127
	v_fma_f32 v119, -v119, v186, v128
	v_div_fmas_f32 v119, v119, v127, v186
	v_div_fixup_f32 v118, v119, v118, 1.0
	v_cvt_pk_f16_f32 v48, v118, v48
	v_cvt_f32_f16_e32 v118, v48
	v_cvt_f32_f16_sdwa v119, v48 dst_sel:DWORD dst_unused:UNUSED_PAD src0_sel:WORD_1
	v_mov_b32_e32 v48, v49
	v_mov_b32_e32 v49, v50
	s_add_u32 s40, s40, 0x120000
	v_pk_fma_f32 v[184:185], v[48:49], v[118:119], v[184:185]
	v_pk_add_f32 v[48:49], v[116:117], 1.0 op_sel_hi:[1,0]
	s_addc_u32 s41, s41, 0
	v_div_scale_f32 v50, s[24:25], v49, v49, 1.0
	v_rcp_f32_e32 v116, v50
	v_fma_mix_f32 v196, v63, v125, v196 op_sel_hi:[0,1,0]
	v_fma_mix_f32 v194, v47, v123, v194 op_sel_hi:[0,1,0]
	v_fma_mix_f32 v192, v31, v121, v192 op_sel_hi:[0,1,0]
	v_fma_f32 v117, -v50, v116, 1.0
	v_fmac_f32_e32 v116, v117, v116
	v_div_scale_f32 v117, vcc, 1.0, v49, 1.0
	v_mul_f32_e32 v118, v117, v116
	v_fma_f32 v119, -v50, v118, v117
	v_fmac_f32_e32 v118, v119, v116
	v_fma_f32 v50, -v50, v118, v117
	v_div_fmas_f32 v50, v50, v116, v118
	v_div_fixup_f32 v49, v50, v49, 1.0
	v_div_scale_f32 v50, s[24:25], v48, v48, 1.0
	v_rcp_f32_e32 v116, v50
	v_fma_mix_f32 v190, v15, v120, v190 op_sel_hi:[0,1,0]
	s_cmp_eq_u32 s45, 3
	v_fma_f32 v117, -v50, v116, 1.0
	v_fmac_f32_e32 v116, v117, v116
	v_div_scale_f32 v117, vcc, 1.0, v48, 1.0
	v_mul_f32_e32 v118, v117, v116
	v_fma_f32 v119, -v50, v118, v117
	v_fmac_f32_e32 v118, v119, v116
	v_fma_f32 v50, -v50, v118, v117
	v_div_fmas_f32 v50, v50, v116, v118
	v_div_fixup_f32 v48, v50, v48, 1.0
	v_cvt_pk_f16_f32 v49, v48, v49
	v_cvt_f32_f16_e32 v48, v49
	v_cvt_f32_f16_sdwa v49, v49 dst_sel:DWORD dst_unused:UNUSED_PAD src0_sel:WORD_1
	v_mov_b32_e32 v50, v51
	v_mov_b32_e32 v51, v52
	s_barrier
	s_cmp_eq_u32 s45, 3
	s_cbranch_scc1 .Lpf_skip
; DI void wait_vm0() { asm volatile("s_waitcnt vmcnt(0)" ::: "memory"); }
; template <int MB, bool SWAP>
; DI void gemm_kloop(f32x16 (&acc)[MB][2], const h16* __restrict__ A, int lda, const h16* __restrict__ B, int ldb, int K, char* lds) {
;     ...
;   auto piece = [&](int p, int kt, int buf) {
;     char* s = lds + buf * STAGE;
;     if (p < MB) __builtin_amdgcn_global_load_lds((const unsigned*)((const char*)(A + (size_t)p * 64 * lda + kt * 64) + voa), (unsigned*)(s + p * 8192 + lofs), 16, 0, 0);
;     else __builtin_amdgcn_global_load_lds((const unsigned*)((const char*)(B + (size_t)(p - MB) * 64 * ldb + kt * 64) + vob), (unsigned*)(s + A_BYTES + (p - MB) * 8192 + lofs), 16, 0, 0);
;   };
;   wait_vm0();
; #pragma unroll
;   for (int p = 0; p < NP; ++p) piece(p, 0, 0);
; #pragma unroll
;   for (int p = 0; p < NP; ++p) piece(p, 1, 1);
; template <int MB>
; DI void merge_tile(const Params& P, int layer, size_t row0, int nt, char* smem) {
;     ...
; #pragma unroll
;     for (int mb = 0; mb < MB; ++mb)
; #pragma unroll
;       for (int nb = 0; nb < 2; ++nb)
; #pragma unroll
;         for (int v = 0; v < 16; ++v) macc[mb][nb][v] += (float)gpk[mb][nb][v >> 3][v & 7] * pa2[mb][nb][v];
	v_mov_b32_e32 v241, 0
	v_mov_b32_e32 v229, v208
	s_lshl_b32 vcc_lo, s45, 10
	v_ashrrev_i32_e32 v235, 3, v229
	v_bfe_u32 v236, v229, 3, 3
	v_and_or_b32 v224, v235, -8, v236
	v_lshrrev_b32_e32 v225, 1, v224
	v_xor_b32_e32 v225, v225, v229
	v_lshlrev_b32_e32 v225, 3, v225
	v_mul_lo_u32 v226, v224, s6
	v_and_b32_e32 v237, 56, v225
	v_or_b32_e32 v225, v237, v226
	v_lshlrev_b32_e32 v240, 1, v225
	v_lshlrev_b32_e32 v225, 4, v229
	v_and_b32_e32 v225, 0x70, v225
	v_lshl_or_b32 v232, v224, 7, v225
	v_add_u32_e32 v234, 0, v232
	v_add_u32_e32 v239, 0x2000, v234
	v_readfirstlane_b32 s33, v234
	s_add_i32 s24, s74, vcc_lo
	s_nop 0
	v_lshl_add_u64 v[226:227], s[50:51], 0, v[240:241]
	s_mov_b32 m0, s33
	s_mov_b64 s[52:53], 0x22000
	v_readfirstlane_b32 s33, v239
	s_mul_i32 s84, s24, 0x440
	global_load_lds_dwordx4 v240, s[50:51]
	v_lshl_add_u64 v[230:231], v[226:227], 0, s[52:53]
	s_mov_b32 m0, s33
	s_lshl_b64 s[24:25], s[84:85], 1
	global_load_lds_dwordx4 v[230:231], off
	v_add_u32_e32 v230, 0x4000, v234
	s_add_u32 s24, s96, s24
	v_and_b32_e32 v224, 31, v229
	v_lshrrev_b32_e32 v225, 2, v229
	v_readfirstlane_b32 s33, v230
	s_addc_u32 s25, s97, s25
	v_and_or_b32 v238, v225, s7, v224
	v_lshlrev_b32_e32 v224, 7, v229
	s_mov_b32 m0, s33
	v_add_u32_e32 v239, 0x6000, v234
	v_and_b32_e32 v228, 0x6f80, v224
	v_lshl_add_u64 v[224:225], s[24:25], 0, v[240:241]
	global_load_lds_dwordx4 v240, s[24:25]
	v_readfirstlane_b32 s24, v239
	v_lshl_add_u64 v[230:231], v[224:225], 0, s[52:53]
	s_mov_b32 m0, s24
	s_mov_b64 s[24:25], 0x44000
	v_add_u32_e32 v239, 0x8000, v234
	global_load_lds_dwordx4 v[230:231], off
	v_lshl_add_u64 v[230:231], v[224:225], 0, s[24:25]
	v_readfirstlane_b32 s24, v239
	s_mov_b32 m0, s24
	s_mov_b64 s[24:25], 0x66000
	v_add_u32_e32 v239, 0xa000, v234
	global_load_lds_dwordx4 v[230:231], off
	v_lshl_add_u64 v[230:231], v[224:225], 0, s[24:25]
	v_readfirstlane_b32 s24, v239
	s_mov_b32 m0, s24
	v_lshl_add_u64 v[226:227], v[226:227], 0, s[22:23]
	global_load_lds_dwordx4 v[230:231], off
	v_add_u32_e32 v231, 0xc000, v234
	v_lshrrev_b32_e32 v233, 1, v229
	v_readfirstlane_b32 s24, v231
	s_mov_b32 m0, s24
	v_add_u32_e32 v231, s8, v232
	global_load_lds_dwordx4 v[226:227], off
	v_add_u32_e32 v226, 0xe000, v234
	v_bfe_u32 v239, v229, 5, 1
	v_readfirstlane_b32 s24, v226
	s_mov_b32 m0, s24
	v_readfirstlane_b32 s24, v231
	global_load_lds_dwordx4 v240, s[86:87]
	v_lshl_add_u64 v[226:227], v[224:225], 0, s[22:23]
	s_mov_b32 m0, s24
	s_mov_b64 s[24:25], 0x22080
	v_add_u32_e32 v231, s9, v232
	global_load_lds_dwordx4 v[226:227], off
	v_lshl_add_u64 v[226:227], v[224:225], 0, s[24:25]
	v_readfirstlane_b32 s24, v231
	s_mov_b32 m0, s24
	s_mov_b64 s[24:25], 0x44080
	v_add_u32_e32 v231, s79, v232
	global_load_lds_dwordx4 v[226:227], off
	v_lshl_add_u64 v[226:227], v[224:225], 0, s[24:25]
	v_readfirstlane_b32 s24, v231
	s_mov_b32 m0, s24
	s_mov_b64 s[24:25], 0x66080
	global_load_lds_dwordx4 v[226:227], off
	v_add_u32_e32 v226, s10, v232
	v_lshl_add_u64 v[224:225], v[224:225], 0, s[24:25]
	v_readfirstlane_b32 s24, v226
	s_mov_b32 m0, s24
	v_lshlrev_b32_e32 v230, 7, v238
	global_load_lds_dwordx4 v[224:225], off
.Lpf_skip:
	v_pk_fma_f32 v[182:183], v[50:51], v[48:49], v[182:183]
	v_pk_add_f32 v[48:49], v[114:115], 1.0 op_sel_hi:[1,0]
	s_nop 0
	v_div_scale_f32 v50, s[24:25], v49, v49, 1.0
	v_rcp_f32_e32 v51, v50
	s_nop 0
	v_fma_f32 v52, -v50, v51, 1.0
	v_fmac_f32_e32 v51, v52, v51
	v_div_scale_f32 v52, vcc, 1.0, v49, 1.0
	v_mul_f32_e32 v114, v52, v51
	v_fma_f32 v115, -v50, v114, v52
	v_fmac_f32_e32 v114, v115, v51
	v_fma_f32 v50, -v50, v114, v52
	v_div_fmas_f32 v50, v50, v51, v114
	v_div_fixup_f32 v49, v50, v49, 1.0
	v_div_scale_f32 v50, s[24:25], v48, v48, 1.0
	v_rcp_f32_e32 v51, v50
	s_nop 0
	v_fma_f32 v52, -v50, v51, 1.0
	v_fmac_f32_e32 v51, v52, v51
	v_div_scale_f32 v52, vcc, 1.0, v48, 1.0
	v_mul_f32_e32 v114, v52, v51
	v_fma_f32 v115, -v50, v114, v52
	v_fmac_f32_e32 v114, v115, v51
	v_fma_f32 v50, -v50, v114, v52
	v_div_fmas_f32 v50, v50, v51, v114
	v_div_fixup_f32 v48, v50, v48, 1.0
	v_cvt_pk_f16_f32 v49, v48, v49
	v_cvt_f32_f16_e32 v48, v49
	v_cvt_f32_f16_sdwa v49, v49 dst_sel:DWORD dst_unused:UNUSED_PAD src0_sel:WORD_1
	v_mov_b32_e32 v50, v53
	v_mov_b32_e32 v51, v54
	v_pk_fma_f32 v[180:181], v[50:51], v[48:49], v[180:181]
	v_pk_add_f32 v[48:49], v[112:113], 1.0 op_sel_hi:[1,0]
	s_nop 0
	v_div_scale_f32 v50, s[24:25], v49, v49, 1.0
	v_rcp_f32_e32 v51, v50
	s_nop 0
	v_fma_f32 v52, -v50, v51, 1.0
	v_fmac_f32_e32 v51, v52, v51
	v_div_scale_f32 v52, vcc, 1.0, v49, 1.0
	v_mul_f32_e32 v53, v52, v51
	v_fma_f32 v54, -v50, v53, v52
	v_fmac_f32_e32 v53, v54, v51
	v_fma_f32 v50, -v50, v53, v52
	v_div_fmas_f32 v50, v50, v51, v53
	v_div_fixup_f32 v49, v50, v49, 1.0
	v_div_scale_f32 v50, s[24:25], v48, v48, 1.0
	v_rcp_f32_e32 v51, v50
	s_nop 0
	v_fma_f32 v52, -v50, v51, 1.0
	v_fmac_f32_e32 v51, v52, v51
	v_div_scale_f32 v52, vcc, 1.0, v48, 1.0
	v_mul_f32_e32 v53, v52, v51
	v_fma_f32 v54, -v50, v53, v52
	v_fmac_f32_e32 v53, v54, v51
	v_fma_f32 v50, -v50, v53, v52
	v_div_fmas_f32 v50, v50, v51, v53
	v_div_fixup_f32 v48, v50, v48, 1.0
	v_cvt_pk_f16_f32 v49, v48, v49
	v_cvt_f32_f16_e32 v48, v49
	v_cvt_f32_f16_sdwa v49, v49 dst_sel:DWORD dst_unused:UNUSED_PAD src0_sel:WORD_1
	v_mov_b32_e32 v50, v55
	v_mov_b32_e32 v51, v56
	v_pk_fma_f32 v[178:179], v[50:51], v[48:49], v[178:179]
	v_pk_add_f32 v[48:49], v[110:111], 1.0 op_sel_hi:[1,0]
	s_nop 0
	v_div_scale_f32 v50, s[24:25], v49, v49, 1.0
	v_rcp_f32_e32 v51, v50
	s_nop 0
	v_fma_f32 v52, -v50, v51, 1.0
	v_fmac_f32_e32 v51, v52, v51
	v_div_scale_f32 v52, vcc, 1.0, v49, 1.0
	v_mul_f32_e32 v53, v52, v51
	v_fma_f32 v54, -v50, v53, v52
; DI float sigmoid_f(float x) { return 1.f / (1.f + __expf(-x)); }
; template <int MB>
; DI void merge_tile(const Params& P, int layer, size_t row0, int nt, char* smem) {
;     ...
; #pragma unroll
;     for (int mb = 0; mb < MB; ++mb)
; #pragma unroll
;       for (int nb = 0; nb < 2; ++nb)
; #pragma unroll
;         for (int v = 0; v < 16; ++v) macc[mb][nb][v] += (float)gpk[mb][nb][v >> 3][v & 7] * pa2[mb][nb][v];
	v_fmac_f32_e32 v53, v54, v51
	v_fma_f32 v50, -v50, v53, v52
	v_div_fmas_f32 v50, v50, v51, v53
	v_div_fixup_f32 v49, v50, v49, 1.0
	v_div_scale_f32 v50, s[24:25], v48, v48, 1.0
	v_rcp_f32_e32 v51, v50
	s_nop 0
	v_fma_f32 v52, -v50, v51, 1.0
	v_fmac_f32_e32 v51, v52, v51
	v_div_scale_f32 v52, vcc, 1.0, v48, 1.0
	v_mul_f32_e32 v53, v52, v51
	v_fma_f32 v54, -v50, v53, v52
	v_fmac_f32_e32 v53, v54, v51
	v_fma_f32 v50, -v50, v53, v52
	v_div_fmas_f32 v50, v50, v51, v53
	v_div_fixup_f32 v48, v50, v48, 1.0
	v_cvt_pk_f16_f32 v49, v48, v49
	v_cvt_f32_f16_e32 v48, v49
	v_cvt_f32_f16_sdwa v49, v49 dst_sel:DWORD dst_unused:UNUSED_PAD src0_sel:WORD_1
	v_mov_b32_e32 v50, v57
	v_mov_b32_e32 v51, v58
	v_pk_fma_f32 v[176:177], v[50:51], v[48:49], v[176:177]
	v_pk_add_f32 v[48:49], v[108:109], 1.0 op_sel_hi:[1,0]
	s_nop 0
	v_div_scale_f32 v50, s[24:25], v49, v49, 1.0
	v_rcp_f32_e32 v51, v50
	s_nop 0
	v_fma_f32 v52, -v50, v51, 1.0
	v_fmac_f32_e32 v51, v52, v51
	v_div_scale_f32 v52, vcc, 1.0, v49, 1.0
	v_mul_f32_e32 v53, v52, v51
	v_fma_f32 v54, -v50, v53, v52
	v_fmac_f32_e32 v53, v54, v51
	v_fma_f32 v50, -v50, v53, v52
	v_div_fmas_f32 v50, v50, v51, v53
	v_div_fixup_f32 v49, v50, v49, 1.0
	v_div_scale_f32 v50, s[24:25], v48, v48, 1.0
	v_rcp_f32_e32 v51, v50
	s_nop 0
	v_fma_f32 v52, -v50, v51, 1.0
	v_fmac_f32_e32 v51, v52, v51
	v_div_scale_f32 v52, vcc, 1.0, v48, 1.0
	v_mul_f32_e32 v53, v52, v51
	v_fma_f32 v54, -v50, v53, v52
	v_fmac_f32_e32 v53, v54, v51
	v_fma_f32 v50, -v50, v53, v52
	v_div_fmas_f32 v50, v50, v51, v53
	v_div_fixup_f32 v48, v50, v48, 1.0
	v_cvt_pk_f16_f32 v49, v48, v49
	v_cvt_f32_f16_e32 v48, v49
	v_cvt_f32_f16_sdwa v49, v49 dst_sel:DWORD dst_unused:UNUSED_PAD src0_sel:WORD_1
	v_mov_b32_e32 v50, v59
	v_mov_b32_e32 v51, v60
	v_pk_fma_f32 v[174:175], v[50:51], v[48:49], v[174:175]
	v_pk_add_f32 v[48:49], v[106:107], 1.0 op_sel_hi:[1,0]
	s_nop 0
	v_div_scale_f32 v50, s[24:25], v49, v49, 1.0
	v_rcp_f32_e32 v51, v50
	s_nop 0
	v_fma_f32 v52, -v50, v51, 1.0
	v_fmac_f32_e32 v51, v52, v51
	v_div_scale_f32 v52, vcc, 1.0, v49, 1.0
	v_mul_f32_e32 v53, v52, v51
	v_fma_f32 v54, -v50, v53, v52
	v_fmac_f32_e32 v53, v54, v51
	v_fma_f32 v50, -v50, v53, v52
	v_div_fmas_f32 v50, v50, v51, v53
	v_div_fixup_f32 v49, v50, v49, 1.0
	v_div_scale_f32 v50, s[24:25], v48, v48, 1.0
	v_rcp_f32_e32 v51, v50
	s_nop 0
	v_fma_f32 v52, -v50, v51, 1.0
	v_fmac_f32_e32 v51, v52, v51
	v_div_scale_f32 v52, vcc, 1.0, v48, 1.0
	v_mul_f32_e32 v53, v52, v51
	v_fma_f32 v54, -v50, v53, v52
	v_fmac_f32_e32 v53, v54, v51
	v_fma_f32 v50, -v50, v53, v52
	v_div_fmas_f32 v50, v50, v51, v53
	v_div_fixup_f32 v48, v50, v48, 1.0
	v_cvt_pk_f16_f32 v49, v48, v49
	v_cvt_f32_f16_e32 v48, v49
	v_cvt_f32_f16_sdwa v49, v49 dst_sel:DWORD dst_unused:UNUSED_PAD src0_sel:WORD_1
	v_mov_b32_e32 v50, v61
	v_mov_b32_e32 v51, v62
	v_pk_fma_f32 v[172:173], v[50:51], v[48:49], v[172:173]
	v_pk_add_f32 v[48:49], v[104:105], 1.0 op_sel_hi:[1,0]
	s_nop 0
	v_div_scale_f32 v32, s[24:25], v49, v49, 1.0
	v_rcp_f32_e32 v50, v32
	s_nop 0
	v_fma_f32 v51, -v32, v50, 1.0
	v_fmac_f32_e32 v50, v51, v50
	v_div_scale_f32 v51, vcc, 1.0, v49, 1.0
	v_mul_f32_e32 v52, v51, v50
	v_fma_f32 v53, -v32, v52, v51
	v_fmac_f32_e32 v52, v53, v50
	v_fma_f32 v32, -v32, v52, v51
	v_div_fmas_f32 v32, v32, v50, v52
	v_div_fixup_f32 v32, v32, v49, 1.0
	v_div_scale_f32 v49, s[24:25], v48, v48, 1.0
	v_rcp_f32_e32 v50, v49
	s_nop 0
	v_fma_f32 v51, -v49, v50, 1.0
	v_fmac_f32_e32 v50, v51, v50
	v_div_scale_f32 v51, vcc, 1.0, v48, 1.0
	v_mul_f32_e32 v52, v51, v50
	v_fma_f32 v53, -v49, v52, v51
	v_fmac_f32_e32 v52, v53, v50
	v_fma_f32 v49, -v49, v52, v51
	v_div_fmas_f32 v49, v49, v50, v52
	v_div_fixup_f32 v48, v49, v48, 1.0
	v_cvt_pk_f16_f32 v32, v48, v32
	v_cvt_f32_f16_e32 v48, v32
	v_cvt_f32_f16_sdwa v49, v32 dst_sel:DWORD dst_unused:UNUSED_PAD src0_sel:WORD_1
	v_mov_b32_e32 v32, v33
	v_mov_b32_e32 v33, v34
	v_pk_fma_f32 v[170:171], v[32:33], v[48:49], v[170:171]
	v_pk_add_f32 v[32:33], v[102:103], 1.0 op_sel_hi:[1,0]
	s_nop 0
	v_div_scale_f32 v34, s[24:25], v33, v33, 1.0
	v_rcp_f32_e32 v48, v34
	s_nop 0
	v_fma_f32 v49, -v34, v48, 1.0
	v_fmac_f32_e32 v48, v49, v48
	v_div_scale_f32 v49, vcc, 1.0, v33, 1.0
	v_mul_f32_e32 v50, v49, v48
	v_fma_f32 v51, -v34, v50, v49
	v_fmac_f32_e32 v50, v51, v48
	v_fma_f32 v34, -v34, v50, v49
	v_div_fmas_f32 v34, v34, v48, v50
	v_div_fixup_f32 v33, v34, v33, 1.0
	v_div_scale_f32 v34, s[24:25], v32, v32, 1.0
	v_rcp_f32_e32 v48, v34
	s_nop 0
	v_fma_f32 v49, -v34, v48, 1.0
	v_fmac_f32_e32 v48, v49, v48
	v_div_scale_f32 v49, vcc, 1.0, v32, 1.0
	v_mul_f32_e32 v50, v49, v48
	v_fma_f32 v51, -v34, v50, v49
	v_fmac_f32_e32 v50, v51, v48
	v_fma_f32 v34, -v34, v50, v49
	v_div_fmas_f32 v34, v34, v48, v50
	v_div_fixup_f32 v32, v34, v32, 1.0
	v_cvt_pk_f16_f32 v33, v32, v33
	v_cvt_f32_f16_e32 v32, v33
	v_cvt_f32_f16_sdwa v33, v33 dst_sel:DWORD dst_unused:UNUSED_PAD src0_sel:WORD_1
	v_mov_b32_e32 v34, v35
	v_mov_b32_e32 v35, v36
	v_pk_fma_f32 v[168:169], v[34:35], v[32:33], v[168:169]
	v_pk_add_f32 v[32:33], v[100:101], 1.0 op_sel_hi:[1,0]
	s_nop 0
	v_div_scale_f32 v34, s[24:25], v33, v33, 1.0
	v_rcp_f32_e32 v35, v34
	s_nop 0
	v_fma_f32 v36, -v34, v35, 1.0
	v_fmac_f32_e32 v35, v36, v35
	v_div_scale_f32 v36, vcc, 1.0, v33, 1.0
	v_mul_f32_e32 v48, v36, v35
	v_fma_f32 v49, -v34, v48, v36
	v_fmac_f32_e32 v48, v49, v35
	v_fma_f32 v34, -v34, v48, v36
	v_div_fmas_f32 v34, v34, v35, v48
	v_div_fixup_f32 v33, v34, v33, 1.0
	v_div_scale_f32 v34, s[24:25], v32, v32, 1.0
	v_rcp_f32_e32 v35, v34
	s_nop 0
	v_fma_f32 v36, -v34, v35, 1.0
	v_fmac_f32_e32 v35, v36, v35
	v_div_scale_f32 v36, vcc, 1.0, v32, 1.0
	v_mul_f32_e32 v48, v36, v35
; DI float sigmoid_f(float x) { return 1.f / (1.f + __expf(-x)); }
; template <int MB>
; DI void merge_tile(const Params& P, int layer, size_t row0, int nt, char* smem) {
;     ...
; #pragma unroll
;     for (int mb = 0; mb < MB; ++mb)
; #pragma unroll
;       for (int nb = 0; nb < 2; ++nb)
; #pragma unroll
;         for (int v = 0; v < 16; ++v) macc[mb][nb][v] += (float)gpk[mb][nb][v >> 3][v & 7] * pa2[mb][nb][v];
	v_fma_f32 v49, -v34, v48, v36
	v_fmac_f32_e32 v48, v49, v35
	v_fma_f32 v34, -v34, v48, v36
	v_div_fmas_f32 v34, v34, v35, v48
	v_div_fixup_f32 v32, v34, v32, 1.0
	v_cvt_pk_f16_f32 v33, v32, v33
	v_cvt_f32_f16_e32 v32, v33
	v_cvt_f32_f16_sdwa v33, v33 dst_sel:DWORD dst_unused:UNUSED_PAD src0_sel:WORD_1
	v_mov_b32_e32 v34, v37
	v_mov_b32_e32 v35, v38
	v_pk_fma_f32 v[166:167], v[34:35], v[32:33], v[166:167]
	v_pk_add_f32 v[32:33], v[98:99], 1.0 op_sel_hi:[1,0]
	s_nop 0
	v_div_scale_f32 v34, s[24:25], v33, v33, 1.0
	v_rcp_f32_e32 v35, v34
	s_nop 0
	v_fma_f32 v36, -v34, v35, 1.0
	v_fmac_f32_e32 v35, v36, v35
	v_div_scale_f32 v36, vcc, 1.0, v33, 1.0
	v_mul_f32_e32 v37, v36, v35
	v_fma_f32 v38, -v34, v37, v36
	v_fmac_f32_e32 v37, v38, v35
	v_fma_f32 v34, -v34, v37, v36
	v_div_fmas_f32 v34, v34, v35, v37
	v_div_fixup_f32 v33, v34, v33, 1.0
	v_div_scale_f32 v34, s[24:25], v32, v32, 1.0
	v_rcp_f32_e32 v35, v34
	s_nop 0
	v_fma_f32 v36, -v34, v35, 1.0
	v_fmac_f32_e32 v35, v36, v35
	v_div_scale_f32 v36, vcc, 1.0, v32, 1.0
	v_mul_f32_e32 v37, v36, v35
	v_fma_f32 v38, -v34, v37, v36
	v_fmac_f32_e32 v37, v38, v35
	v_fma_f32 v34, -v34, v37, v36
	v_div_fmas_f32 v34, v34, v35, v37
	v_div_fixup_f32 v32, v34, v32, 1.0
	v_cvt_pk_f16_f32 v33, v32, v33
	v_cvt_f32_f16_e32 v32, v33
	v_cvt_f32_f16_sdwa v33, v33 dst_sel:DWORD dst_unused:UNUSED_PAD src0_sel:WORD_1
	v_mov_b32_e32 v34, v39
	v_mov_b32_e32 v35, v40
	v_pk_fma_f32 v[164:165], v[34:35], v[32:33], v[164:165]
	v_pk_add_f32 v[32:33], v[96:97], 1.0 op_sel_hi:[1,0]
	s_nop 0
	v_div_scale_f32 v34, s[24:25], v33, v33, 1.0
	v_rcp_f32_e32 v35, v34
	s_nop 0
	v_fma_f32 v36, -v34, v35, 1.0
	v_fmac_f32_e32 v35, v36, v35
	v_div_scale_f32 v36, vcc, 1.0, v33, 1.0
	v_mul_f32_e32 v37, v36, v35
	v_fma_f32 v38, -v34, v37, v36
	v_fmac_f32_e32 v37, v38, v35
	v_fma_f32 v34, -v34, v37, v36
	v_div_fmas_f32 v34, v34, v35, v37
	v_div_fixup_f32 v33, v34, v33, 1.0
	v_div_scale_f32 v34, s[24:25], v32, v32, 1.0
	v_rcp_f32_e32 v35, v34
	s_nop 0
	v_fma_f32 v36, -v34, v35, 1.0
	v_fmac_f32_e32 v35, v36, v35
	v_div_scale_f32 v36, vcc, 1.0, v32, 1.0
	v_mul_f32_e32 v37, v36, v35
	v_fma_f32 v38, -v34, v37, v36
	v_fmac_f32_e32 v37, v38, v35
	v_fma_f32 v34, -v34, v37, v36
	v_div_fmas_f32 v34, v34, v35, v37
	v_div_fixup_f32 v32, v34, v32, 1.0
	v_cvt_pk_f16_f32 v33, v32, v33
	v_cvt_f32_f16_e32 v32, v33
	v_cvt_f32_f16_sdwa v33, v33 dst_sel:DWORD dst_unused:UNUSED_PAD src0_sel:WORD_1
	v_mov_b32_e32 v34, v41
	v_mov_b32_e32 v35, v42
	v_pk_fma_f32 v[162:163], v[34:35], v[32:33], v[162:163]
	v_pk_add_f32 v[32:33], v[94:95], 1.0 op_sel_hi:[1,0]
	s_nop 0
	v_div_scale_f32 v34, s[24:25], v33, v33, 1.0
	v_rcp_f32_e32 v35, v34
	s_nop 0
	v_fma_f32 v36, -v34, v35, 1.0
	v_fmac_f32_e32 v35, v36, v35
	v_div_scale_f32 v36, vcc, 1.0, v33, 1.0
	v_mul_f32_e32 v37, v36, v35
	v_fma_f32 v38, -v34, v37, v36
	v_fmac_f32_e32 v37, v38, v35
	v_fma_f32 v34, -v34, v37, v36
	v_div_fmas_f32 v34, v34, v35, v37
	v_div_fixup_f32 v33, v34, v33, 1.0
	v_div_scale_f32 v34, s[24:25], v32, v32, 1.0
	v_rcp_f32_e32 v35, v34
	s_nop 0
	v_fma_f32 v36, -v34, v35, 1.0
	v_fmac_f32_e32 v35, v36, v35
	v_div_scale_f32 v36, vcc, 1.0, v32, 1.0
	v_mul_f32_e32 v37, v36, v35
	v_fma_f32 v38, -v34, v37, v36
	v_fmac_f32_e32 v37, v38, v35
	v_fma_f32 v34, -v34, v37, v36
	v_div_fmas_f32 v34, v34, v35, v37
	v_div_fixup_f32 v32, v34, v32, 1.0
	v_cvt_pk_f16_f32 v33, v32, v33
	v_cvt_f32_f16_e32 v32, v33
	v_cvt_f32_f16_sdwa v33, v33 dst_sel:DWORD dst_unused:UNUSED_PAD src0_sel:WORD_1
	v_mov_b32_e32 v34, v43
	v_mov_b32_e32 v35, v44
	v_pk_fma_f32 v[160:161], v[34:35], v[32:33], v[160:161]
	v_pk_add_f32 v[32:33], v[92:93], 1.0 op_sel_hi:[1,0]
	s_nop 0
	v_div_scale_f32 v34, s[24:25], v33, v33, 1.0
	v_rcp_f32_e32 v35, v34
	s_nop 0
	v_fma_f32 v36, -v34, v35, 1.0
	v_fmac_f32_e32 v35, v36, v35
	v_div_scale_f32 v36, vcc, 1.0, v33, 1.0
	v_mul_f32_e32 v37, v36, v35
	v_fma_f32 v38, -v34, v37, v36
	v_fmac_f32_e32 v37, v38, v35
	v_fma_f32 v34, -v34, v37, v36
	v_div_fmas_f32 v34, v34, v35, v37
	v_div_fixup_f32 v33, v34, v33, 1.0
	v_div_scale_f32 v34, s[24:25], v32, v32, 1.0
	v_rcp_f32_e32 v35, v34
	s_nop 0
	v_fma_f32 v36, -v34, v35, 1.0
	v_fmac_f32_e32 v35, v36, v35
	v_div_scale_f32 v36, vcc, 1.0, v32, 1.0
	v_mul_f32_e32 v37, v36, v35
	v_fma_f32 v38, -v34, v37, v36
	v_fmac_f32_e32 v37, v38, v35
	v_fma_f32 v34, -v34, v37, v36
	v_div_fmas_f32 v34, v34, v35, v37
	v_div_fixup_f32 v32, v34, v32, 1.0
	v_cvt_pk_f16_f32 v33, v32, v33
	v_cvt_f32_f16_e32 v32, v33
	v_cvt_f32_f16_sdwa v33, v33 dst_sel:DWORD dst_unused:UNUSED_PAD src0_sel:WORD_1
	v_mov_b32_e32 v34, v45
	v_mov_b32_e32 v35, v46
	v_pk_fma_f32 v[158:159], v[34:35], v[32:33], v[158:159]
	v_pk_add_f32 v[32:33], v[90:91], 1.0 op_sel_hi:[1,0]
	s_nop 0
	v_div_scale_f32 v16, s[24:25], v33, v33, 1.0
	v_rcp_f32_e32 v34, v16
	s_nop 0
	v_fma_f32 v35, -v16, v34, 1.0
	v_fmac_f32_e32 v34, v35, v34
	v_div_scale_f32 v35, vcc, 1.0, v33, 1.0
	v_mul_f32_e32 v36, v35, v34
	v_fma_f32 v37, -v16, v36, v35
	v_fmac_f32_e32 v36, v37, v34
	v_fma_f32 v16, -v16, v36, v35
	v_div_fmas_f32 v16, v16, v34, v36
	v_div_fixup_f32 v16, v16, v33, 1.0
	v_div_scale_f32 v33, s[24:25], v32, v32, 1.0
	v_rcp_f32_e32 v34, v33
	s_nop 0
	v_fma_f32 v35, -v33, v34, 1.0
	v_fmac_f32_e32 v34, v35, v34
	v_div_scale_f32 v35, vcc, 1.0, v32, 1.0
	v_mul_f32_e32 v36, v35, v34
	v_fma_f32 v37, -v33, v36, v35
	v_fmac_f32_e32 v36, v37, v34
	v_fma_f32 v33, -v33, v36, v35
	v_div_fmas_f32 v33, v33, v34, v36
	v_div_fixup_f32 v32, v33, v32, 1.0
	v_cvt_pk_f16_f32 v16, v32, v16
	v_cvt_f32_f16_e32 v32, v16
	v_cvt_f32_f16_sdwa v33, v16 dst_sel:DWORD dst_unused:UNUSED_PAD src0_sel:WORD_1
	v_mov_b32_e32 v16, v17
	v_mov_b32_e32 v17, v18
; DI float sigmoid_f(float x) { return 1.f / (1.f + __expf(-x)); }
; template <int MB>
; DI void merge_tile(const Params& P, int layer, size_t row0, int nt, char* smem) {
;     ...
; #pragma unroll
;     for (int mb = 0; mb < MB; ++mb)
; #pragma unroll
;       for (int nb = 0; nb < 2; ++nb)
; #pragma unroll
;         for (int v = 0; v < 16; ++v) macc[mb][nb][v] += (float)gpk[mb][nb][v >> 3][v & 7] * pa2[mb][nb][v];
	v_pk_fma_f32 v[156:157], v[16:17], v[32:33], v[156:157]
	v_pk_add_f32 v[16:17], v[88:89], 1.0 op_sel_hi:[1,0]
	s_nop 0
	v_div_scale_f32 v18, s[24:25], v17, v17, 1.0
	v_rcp_f32_e32 v32, v18
	s_nop 0
	v_fma_f32 v33, -v18, v32, 1.0
	v_fmac_f32_e32 v32, v33, v32
	v_div_scale_f32 v33, vcc, 1.0, v17, 1.0
	v_mul_f32_e32 v34, v33, v32
	v_fma_f32 v35, -v18, v34, v33
	v_fmac_f32_e32 v34, v35, v32
	v_fma_f32 v18, -v18, v34, v33
	v_div_fmas_f32 v18, v18, v32, v34
	v_div_fixup_f32 v17, v18, v17, 1.0
	v_div_scale_f32 v18, s[24:25], v16, v16, 1.0
	v_rcp_f32_e32 v32, v18
	s_nop 0
	v_fma_f32 v33, -v18, v32, 1.0
	v_fmac_f32_e32 v32, v33, v32
	v_div_scale_f32 v33, vcc, 1.0, v16, 1.0
	v_mul_f32_e32 v34, v33, v32
	v_fma_f32 v35, -v18, v34, v33
	v_fmac_f32_e32 v34, v35, v32
	v_fma_f32 v18, -v18, v34, v33
	v_div_fmas_f32 v18, v18, v32, v34
	v_div_fixup_f32 v16, v18, v16, 1.0
	v_cvt_pk_f16_f32 v17, v16, v17
	v_cvt_f32_f16_e32 v16, v17
	v_cvt_f32_f16_sdwa v17, v17 dst_sel:DWORD dst_unused:UNUSED_PAD src0_sel:WORD_1
	v_mov_b32_e32 v18, v19
	v_mov_b32_e32 v19, v20
	v_pk_fma_f32 v[154:155], v[18:19], v[16:17], v[154:155]
	v_pk_add_f32 v[16:17], v[86:87], 1.0 op_sel_hi:[1,0]
	s_nop 0
	v_div_scale_f32 v18, s[24:25], v17, v17, 1.0
	v_rcp_f32_e32 v19, v18
	s_nop 0
	v_fma_f32 v20, -v18, v19, 1.0
	v_fmac_f32_e32 v19, v20, v19
	v_div_scale_f32 v20, vcc, 1.0, v17, 1.0
	v_mul_f32_e32 v32, v20, v19
	v_fma_f32 v33, -v18, v32, v20
	v_fmac_f32_e32 v32, v33, v19
	v_fma_f32 v18, -v18, v32, v20
	v_div_fmas_f32 v18, v18, v19, v32
	v_div_fixup_f32 v17, v18, v17, 1.0
	v_div_scale_f32 v18, s[24:25], v16, v16, 1.0
	v_rcp_f32_e32 v19, v18
	s_nop 0
	v_fma_f32 v20, -v18, v19, 1.0
	v_fmac_f32_e32 v19, v20, v19
	v_div_scale_f32 v20, vcc, 1.0, v16, 1.0
	v_mul_f32_e32 v32, v20, v19
	v_fma_f32 v33, -v18, v32, v20
	v_fmac_f32_e32 v32, v33, v19
	v_fma_f32 v18, -v18, v32, v20
	v_div_fmas_f32 v18, v18, v19, v32
	v_div_fixup_f32 v16, v18, v16, 1.0
	v_cvt_pk_f16_f32 v17, v16, v17
	v_cvt_f32_f16_e32 v16, v17
	v_cvt_f32_f16_sdwa v17, v17 dst_sel:DWORD dst_unused:UNUSED_PAD src0_sel:WORD_1
	v_mov_b32_e32 v18, v21
	v_mov_b32_e32 v19, v22
	v_pk_fma_f32 v[152:153], v[18:19], v[16:17], v[152:153]
	v_pk_add_f32 v[16:17], v[84:85], 1.0 op_sel_hi:[1,0]
	s_nop 0
	v_div_scale_f32 v18, s[24:25], v17, v17, 1.0
	v_rcp_f32_e32 v19, v18
	s_nop 0
	v_fma_f32 v20, -v18, v19, 1.0
	v_fmac_f32_e32 v19, v20, v19
	v_div_scale_f32 v20, vcc, 1.0, v17, 1.0
	v_mul_f32_e32 v21, v20, v19
	v_fma_f32 v22, -v18, v21, v20
	v_fmac_f32_e32 v21, v22, v19
	v_fma_f32 v18, -v18, v21, v20
	v_div_fmas_f32 v18, v18, v19, v21
	v_div_fixup_f32 v17, v18, v17, 1.0
	v_div_scale_f32 v18, s[24:25], v16, v16, 1.0
	v_rcp_f32_e32 v19, v18
	s_nop 0
	v_fma_f32 v20, -v18, v19, 1.0
	v_fmac_f32_e32 v19, v20, v19
	v_div_scale_f32 v20, vcc, 1.0, v16, 1.0
	v_mul_f32_e32 v21, v20, v19
	v_fma_f32 v22, -v18, v21, v20
	v_fmac_f32_e32 v21, v22, v19
	v_fma_f32 v18, -v18, v21, v20
	v_div_fmas_f32 v18, v18, v19, v21
	v_div_fixup_f32 v16, v18, v16, 1.0
	v_cvt_pk_f16_f32 v17, v16, v17
	v_cvt_f32_f16_e32 v16, v17
	v_cvt_f32_f16_sdwa v17, v17 dst_sel:DWORD dst_unused:UNUSED_PAD src0_sel:WORD_1
	v_mov_b32_e32 v18, v23
	v_mov_b32_e32 v19, v24
	v_pk_fma_f32 v[150:151], v[18:19], v[16:17], v[150:151]
	v_pk_add_f32 v[16:17], v[82:83], 1.0 op_sel_hi:[1,0]
	s_nop 0
	v_div_scale_f32 v18, s[24:25], v17, v17, 1.0
	v_rcp_f32_e32 v19, v18
	s_nop 0
	v_fma_f32 v20, -v18, v19, 1.0
	v_fmac_f32_e32 v19, v20, v19
	v_div_scale_f32 v20, vcc, 1.0, v17, 1.0
	v_mul_f32_e32 v21, v20, v19
	v_fma_f32 v22, -v18, v21, v20
	v_fmac_f32_e32 v21, v22, v19
	v_fma_f32 v18, -v18, v21, v20
	v_div_fmas_f32 v18, v18, v19, v21
	v_div_fixup_f32 v17, v18, v17, 1.0
	v_div_scale_f32 v18, s[24:25], v16, v16, 1.0
	v_rcp_f32_e32 v19, v18
	s_nop 0
	v_fma_f32 v20, -v18, v19, 1.0
	v_fmac_f32_e32 v19, v20, v19
	v_div_scale_f32 v20, vcc, 1.0, v16, 1.0
	v_mul_f32_e32 v21, v20, v19
	v_fma_f32 v22, -v18, v21, v20
	v_fmac_f32_e32 v21, v22, v19
	v_fma_f32 v18, -v18, v21, v20
	v_div_fmas_f32 v18, v18, v19, v21
	v_div_fixup_f32 v16, v18, v16, 1.0
	v_cvt_pk_f16_f32 v17, v16, v17
	v_cvt_f32_f16_e32 v16, v17
	v_cvt_f32_f16_sdwa v17, v17 dst_sel:DWORD dst_unused:UNUSED_PAD src0_sel:WORD_1
	v_mov_b32_e32 v18, v25
	v_mov_b32_e32 v19, v26
	v_pk_fma_f32 v[148:149], v[18:19], v[16:17], v[148:149]
	v_pk_add_f32 v[16:17], v[80:81], 1.0 op_sel_hi:[1,0]
	s_nop 0
	v_div_scale_f32 v18, s[24:25], v17, v17, 1.0
	v_rcp_f32_e32 v19, v18
	s_nop 0
	v_fma_f32 v20, -v18, v19, 1.0
	v_fmac_f32_e32 v19, v20, v19
	v_div_scale_f32 v20, vcc, 1.0, v17, 1.0
	v_mul_f32_e32 v21, v20, v19
	v_fma_f32 v22, -v18, v21, v20
	v_fmac_f32_e32 v21, v22, v19
	v_fma_f32 v18, -v18, v21, v20
	v_div_fmas_f32 v18, v18, v19, v21
	v_div_fixup_f32 v17, v18, v17, 1.0
	v_div_scale_f32 v18, s[24:25], v16, v16, 1.0
	v_rcp_f32_e32 v19, v18
	s_nop 0
	v_fma_f32 v20, -v18, v19, 1.0
	v_fmac_f32_e32 v19, v20, v19
	v_div_scale_f32 v20, vcc, 1.0, v16, 1.0
	v_mul_f32_e32 v21, v20, v19
	v_fma_f32 v22, -v18, v21, v20
	v_fmac_f32_e32 v21, v22, v19
	v_fma_f32 v18, -v18, v21, v20
	v_div_fmas_f32 v18, v18, v19, v21
	v_div_fixup_f32 v16, v18, v16, 1.0
	v_cvt_pk_f16_f32 v17, v16, v17
	v_cvt_f32_f16_e32 v16, v17
	v_cvt_f32_f16_sdwa v17, v17 dst_sel:DWORD dst_unused:UNUSED_PAD src0_sel:WORD_1
	v_mov_b32_e32 v18, v27
	v_mov_b32_e32 v19, v28
	v_pk_fma_f32 v[146:147], v[18:19], v[16:17], v[146:147]
	v_pk_add_f32 v[16:17], v[78:79], 1.0 op_sel_hi:[1,0]
	s_nop 0
	v_div_scale_f32 v18, s[24:25], v17, v17, 1.0
	v_rcp_f32_e32 v19, v18
	s_nop 0
	v_fma_f32 v20, -v18, v19, 1.0
	v_fmac_f32_e32 v19, v20, v19
	v_div_scale_f32 v20, vcc, 1.0, v17, 1.0
	v_mul_f32_e32 v21, v20, v19
	v_fma_f32 v22, -v18, v21, v20
; DI float sigmoid_f(float x) { return 1.f / (1.f + __expf(-x)); }
; template <int MB>
; DI void merge_tile(const Params& P, int layer, size_t row0, int nt, char* smem) {
;     ...
; #pragma unroll
;     for (int mb = 0; mb < MB; ++mb)
; #pragma unroll
;       for (int nb = 0; nb < 2; ++nb)
; #pragma unroll
;         for (int v = 0; v < 16; ++v) macc[mb][nb][v] += (float)gpk[mb][nb][v >> 3][v & 7] * pa2[mb][nb][v];
	v_fmac_f32_e32 v21, v22, v19
	v_fma_f32 v18, -v18, v21, v20
	v_div_fmas_f32 v18, v18, v19, v21
	v_div_fixup_f32 v17, v18, v17, 1.0
	v_div_scale_f32 v18, s[24:25], v16, v16, 1.0
	v_rcp_f32_e32 v19, v18
	s_nop 0
	v_fma_f32 v20, -v18, v19, 1.0
	v_fmac_f32_e32 v19, v20, v19
	v_div_scale_f32 v20, vcc, 1.0, v16, 1.0
	v_mul_f32_e32 v21, v20, v19
	v_fma_f32 v22, -v18, v21, v20
	v_fmac_f32_e32 v21, v22, v19
	v_fma_f32 v18, -v18, v21, v20
	v_div_fmas_f32 v18, v18, v19, v21
	v_div_fixup_f32 v16, v18, v16, 1.0
	v_cvt_pk_f16_f32 v17, v16, v17
	v_cvt_f32_f16_e32 v16, v17
	v_cvt_f32_f16_sdwa v17, v17 dst_sel:DWORD dst_unused:UNUSED_PAD src0_sel:WORD_1
	v_mov_b32_e32 v18, v29
	v_mov_b32_e32 v19, v30
	v_pk_fma_f32 v[144:145], v[18:19], v[16:17], v[144:145]
	v_pk_add_f32 v[16:17], v[76:77], 1.0 op_sel_hi:[1,0]
	s_nop 0
	v_div_scale_f32 v0, s[24:25], v17, v17, 1.0
	v_rcp_f32_e32 v18, v0
	s_nop 0
	v_fma_f32 v19, -v0, v18, 1.0
	v_fmac_f32_e32 v18, v19, v18
	v_div_scale_f32 v19, vcc, 1.0, v17, 1.0
	v_mul_f32_e32 v20, v19, v18
	v_fma_f32 v21, -v0, v20, v19
	v_fmac_f32_e32 v20, v21, v18
	v_fma_f32 v0, -v0, v20, v19
	v_div_fmas_f32 v0, v0, v18, v20
	v_div_fixup_f32 v0, v0, v17, 1.0
	v_div_scale_f32 v17, s[24:25], v16, v16, 1.0
	v_rcp_f32_e32 v18, v17
	s_nop 0
	v_fma_f32 v19, -v17, v18, 1.0
	v_fmac_f32_e32 v18, v19, v18
	v_div_scale_f32 v19, vcc, 1.0, v16, 1.0
	v_mul_f32_e32 v20, v19, v18
	v_fma_f32 v21, -v17, v20, v19
	v_fmac_f32_e32 v20, v21, v18
	v_fma_f32 v17, -v17, v20, v19
	v_div_fmas_f32 v17, v17, v18, v20
	v_div_fixup_f32 v16, v17, v16, 1.0
	v_cvt_pk_f16_f32 v0, v16, v0
	v_cvt_f32_f16_e32 v16, v0
	v_cvt_f32_f16_sdwa v17, v0 dst_sel:DWORD dst_unused:UNUSED_PAD src0_sel:WORD_1
	v_mov_b32_e32 v0, v1
	v_mov_b32_e32 v1, v2
	v_pk_fma_f32 v[142:143], v[0:1], v[16:17], v[142:143]
	v_pk_add_f32 v[0:1], v[74:75], 1.0 op_sel_hi:[1,0]
	s_nop 0
	v_div_scale_f32 v2, s[24:25], v1, v1, 1.0
	v_rcp_f32_e32 v16, v2
	s_nop 0
	v_fma_f32 v17, -v2, v16, 1.0
	v_fmac_f32_e32 v16, v17, v16
	v_div_scale_f32 v17, vcc, 1.0, v1, 1.0
	v_mul_f32_e32 v18, v17, v16
	v_fma_f32 v19, -v2, v18, v17
	v_fmac_f32_e32 v18, v19, v16
	v_fma_f32 v2, -v2, v18, v17
	v_div_fmas_f32 v2, v2, v16, v18
	v_div_fixup_f32 v1, v2, v1, 1.0
	v_div_scale_f32 v2, s[24:25], v0, v0, 1.0
	v_rcp_f32_e32 v16, v2
	s_nop 0
	v_fma_f32 v17, -v2, v16, 1.0
	v_fmac_f32_e32 v16, v17, v16
	v_div_scale_f32 v17, vcc, 1.0, v0, 1.0
	v_mul_f32_e32 v18, v17, v16
	v_fma_f32 v19, -v2, v18, v17
	v_fmac_f32_e32 v18, v19, v16
	v_fma_f32 v2, -v2, v18, v17
	v_div_fmas_f32 v2, v2, v16, v18
	v_div_fixup_f32 v0, v2, v0, 1.0
	v_cvt_pk_f16_f32 v1, v0, v1
	v_cvt_f32_f16_e32 v0, v1
	v_cvt_f32_f16_sdwa v1, v1 dst_sel:DWORD dst_unused:UNUSED_PAD src0_sel:WORD_1
	v_mov_b32_e32 v2, v3
	v_mov_b32_e32 v3, v4
	v_pk_fma_f32 v[140:141], v[2:3], v[0:1], v[140:141]
	v_pk_add_f32 v[0:1], v[72:73], 1.0 op_sel_hi:[1,0]
	s_nop 0
	v_div_scale_f32 v2, s[24:25], v1, v1, 1.0
	v_rcp_f32_e32 v3, v2
	s_nop 0
	v_fma_f32 v4, -v2, v3, 1.0
	v_fmac_f32_e32 v3, v4, v3
	v_div_scale_f32 v4, vcc, 1.0, v1, 1.0
	v_mul_f32_e32 v16, v4, v3
	v_fma_f32 v17, -v2, v16, v4
	v_fmac_f32_e32 v16, v17, v3
	v_fma_f32 v2, -v2, v16, v4
	v_div_fmas_f32 v2, v2, v3, v16
	v_div_fixup_f32 v1, v2, v1, 1.0
	v_div_scale_f32 v2, s[24:25], v0, v0, 1.0
	v_rcp_f32_e32 v3, v2
	s_nop 0
	v_fma_f32 v4, -v2, v3, 1.0
	v_fmac_f32_e32 v3, v4, v3
	v_div_scale_f32 v4, vcc, 1.0, v0, 1.0
	v_mul_f32_e32 v16, v4, v3
	v_fma_f32 v17, -v2, v16, v4
	v_fmac_f32_e32 v16, v17, v3
	v_fma_f32 v2, -v2, v16, v4
	v_div_fmas_f32 v2, v2, v3, v16
	v_div_fixup_f32 v0, v2, v0, 1.0
	v_cvt_pk_f16_f32 v1, v0, v1
	v_cvt_f32_f16_e32 v0, v1
	v_cvt_f32_f16_sdwa v1, v1 dst_sel:DWORD dst_unused:UNUSED_PAD src0_sel:WORD_1
	v_mov_b32_e32 v2, v5
	v_mov_b32_e32 v3, v6
	v_pk_fma_f32 v[138:139], v[2:3], v[0:1], v[138:139]
	v_pk_add_f32 v[0:1], v[70:71], 1.0 op_sel_hi:[1,0]
	s_nop 0
	v_div_scale_f32 v2, s[24:25], v1, v1, 1.0
	v_rcp_f32_e32 v3, v2
	s_nop 0
	v_fma_f32 v4, -v2, v3, 1.0
	v_fmac_f32_e32 v3, v4, v3
	v_div_scale_f32 v4, vcc, 1.0, v1, 1.0
	v_mul_f32_e32 v5, v4, v3
	v_fma_f32 v6, -v2, v5, v4
	v_fmac_f32_e32 v5, v6, v3
	v_fma_f32 v2, -v2, v5, v4
	v_div_fmas_f32 v2, v2, v3, v5
	v_div_fixup_f32 v1, v2, v1, 1.0
	v_div_scale_f32 v2, s[24:25], v0, v0, 1.0
	v_rcp_f32_e32 v3, v2
	s_nop 0
	v_fma_f32 v4, -v2, v3, 1.0
	v_fmac_f32_e32 v3, v4, v3
	v_div_scale_f32 v4, vcc, 1.0, v0, 1.0
	v_mul_f32_e32 v5, v4, v3
	v_fma_f32 v6, -v2, v5, v4
	v_fmac_f32_e32 v5, v6, v3
	v_fma_f32 v2, -v2, v5, v4
	v_div_fmas_f32 v2, v2, v3, v5
	v_div_fixup_f32 v0, v2, v0, 1.0
	v_cvt_pk_f16_f32 v1, v0, v1
	v_cvt_f32_f16_e32 v0, v1
	v_cvt_f32_f16_sdwa v1, v1 dst_sel:DWORD dst_unused:UNUSED_PAD src0_sel:WORD_1
	v_mov_b32_e32 v2, v7
	v_mov_b32_e32 v3, v8
	v_pk_fma_f32 v[136:137], v[2:3], v[0:1], v[136:137]
	v_pk_add_f32 v[0:1], v[68:69], 1.0 op_sel_hi:[1,0]
	s_nop 0
	v_div_scale_f32 v2, s[24:25], v1, v1, 1.0
	v_rcp_f32_e32 v3, v2
	s_nop 0
	v_fma_f32 v4, -v2, v3, 1.0
	v_fmac_f32_e32 v3, v4, v3
	v_div_scale_f32 v4, vcc, 1.0, v1, 1.0
	v_mul_f32_e32 v5, v4, v3
	v_fma_f32 v6, -v2, v5, v4
	v_fmac_f32_e32 v5, v6, v3
	v_fma_f32 v2, -v2, v5, v4
	v_div_fmas_f32 v2, v2, v3, v5
	v_div_fixup_f32 v1, v2, v1, 1.0
	v_div_scale_f32 v2, s[24:25], v0, v0, 1.0
	v_rcp_f32_e32 v3, v2
	s_nop 0
	v_fma_f32 v4, -v2, v3, 1.0
	v_fmac_f32_e32 v3, v4, v3
	v_div_scale_f32 v4, vcc, 1.0, v0, 1.0
	v_mul_f32_e32 v5, v4, v3
	v_fma_f32 v6, -v2, v5, v4
	v_fmac_f32_e32 v5, v6, v3
	v_fma_f32 v2, -v2, v5, v4
	v_div_fmas_f32 v2, v2, v3, v5
	v_div_fixup_f32 v0, v2, v0, 1.0
	v_cvt_pk_f16_f32 v1, v0, v1
	v_cvt_f32_f16_e32 v0, v1
	v_cvt_f32_f16_sdwa v1, v1 dst_sel:DWORD dst_unused:UNUSED_PAD src0_sel:WORD_1
	v_mov_b32_e32 v2, v9
; DI int otid() { int t = threadIdx.x; asm volatile("" : "+v"(t)); return t; }
; template <int MB>
; DI void merge_tile(const Params& P, int layer, size_t row0, int nt, char* smem) {
;     ...
; #pragma unroll
;     for (int mb = 0; mb < MB; ++mb)
; #pragma unroll
;       for (int nb = 0; nb < 2; ++nb)
; #pragma unroll
;         for (int v = 0; v < 16; ++v) macc[mb][nb][v] += (float)gpk[mb][nb][v >> 3][v & 7] * pa2[mb][nb][v];
;   }
;   const int tid = otid(), lane = tid & 63, w = tid >> 6, wr = w >> 2, wc = w & 3, r32 = lane & 31, hh = lane >> 5;
; #pragma unroll
;   for (int mb = 0; mb < MB; ++mb) {
;     const size_t row = row0 + wr * 32 * MB + mb * 32 + r32;
; #pragma unroll
;     for (int nb = 0; nb < 2; ++nb)
; #pragma unroll
;       for (int g = 0; g < 4; ++g)
;         *(half4*)(mg + row * LDH + nt * 256 + wc * 64 + nb * 32 + 8 * g + 4 * hh) =
;             cvt4(macc[mb][nb][4 * g], macc[mb][nb][4 * g + 1], macc[mb][nb][4 * g + 2], macc[mb][nb][4 * g + 3]);
;   }
	v_mov_b32_e32 v3, v10
	v_pk_fma_f32 v[134:135], v[2:3], v[0:1], v[134:135]
	v_pk_add_f32 v[0:1], v[66:67], 1.0 op_sel_hi:[1,0]
	s_nop 0
	v_div_scale_f32 v2, s[24:25], v1, v1, 1.0
	v_rcp_f32_e32 v3, v2
	s_nop 0
	v_fma_f32 v4, -v2, v3, 1.0
	v_fmac_f32_e32 v3, v4, v3
	v_div_scale_f32 v4, vcc, 1.0, v1, 1.0
	v_mul_f32_e32 v5, v4, v3
	v_fma_f32 v6, -v2, v5, v4
	v_fmac_f32_e32 v5, v6, v3
	v_fma_f32 v2, -v2, v5, v4
	v_div_fmas_f32 v2, v2, v3, v5
	v_div_fixup_f32 v1, v2, v1, 1.0
	v_div_scale_f32 v2, s[24:25], v0, v0, 1.0
	v_rcp_f32_e32 v3, v2
	s_nop 0
	v_fma_f32 v4, -v2, v3, 1.0
	v_fmac_f32_e32 v3, v4, v3
	v_div_scale_f32 v4, vcc, 1.0, v0, 1.0
	v_mul_f32_e32 v5, v4, v3
	v_fma_f32 v6, -v2, v5, v4
	v_fmac_f32_e32 v5, v6, v3
	v_fma_f32 v2, -v2, v5, v4
	v_div_fmas_f32 v2, v2, v3, v5
	v_div_fixup_f32 v0, v2, v0, 1.0
	v_cvt_pk_f16_f32 v1, v0, v1
	v_cvt_f32_f16_e32 v0, v1
	v_cvt_f32_f16_sdwa v1, v1 dst_sel:DWORD dst_unused:UNUSED_PAD src0_sel:WORD_1
	v_mov_b32_e32 v2, v11
	v_mov_b32_e32 v3, v12
	v_pk_fma_f32 v[132:133], v[2:3], v[0:1], v[132:133]
	v_pk_add_f32 v[0:1], v[64:65], 1.0 op_sel_hi:[1,0]
	s_nop 0
	v_div_scale_f32 v2, s[24:25], v1, v1, 1.0
	v_rcp_f32_e32 v3, v2
	s_nop 0
	v_fma_f32 v4, -v2, v3, 1.0
	v_fmac_f32_e32 v3, v4, v3
	v_div_scale_f32 v4, vcc, 1.0, v1, 1.0
	v_mul_f32_e32 v5, v4, v3
	v_fma_f32 v6, -v2, v5, v4
	v_fmac_f32_e32 v5, v6, v3
	v_fma_f32 v2, -v2, v5, v4
	v_div_fmas_f32 v2, v2, v3, v5
	v_div_fixup_f32 v1, v2, v1, 1.0
	v_div_scale_f32 v2, s[24:25], v0, v0, 1.0
	v_rcp_f32_e32 v3, v2
	s_nop 0
	v_fma_f32 v4, -v2, v3, 1.0
	v_fmac_f32_e32 v3, v4, v3
	v_div_scale_f32 v4, vcc, 1.0, v0, 1.0
	v_mul_f32_e32 v5, v4, v3
	v_fma_f32 v6, -v2, v5, v4
	v_fmac_f32_e32 v5, v6, v3
	v_fma_f32 v2, -v2, v5, v4
	v_div_fmas_f32 v2, v2, v3, v5
	v_div_fixup_f32 v0, v2, v0, 1.0
	v_cvt_pk_f16_f32 v1, v0, v1
	v_cvt_f32_f16_e32 v0, v1
	v_cvt_f32_f16_sdwa v1, v1 dst_sel:DWORD dst_unused:UNUSED_PAD src0_sel:WORD_1
	v_mov_b32_e32 v2, v13
	v_mov_b32_e32 v3, v14
	v_pk_fma_f32 v[130:131], v[2:3], v[0:1], v[130:131]
	s_cmp_eq_u32 s45, 3
	s_cbranch_scc0 .Lhead_pf
	s_lshl_b64 s[2:3], s[46:47], 7
	v_mov_b32_e32 v4, v208
	v_mov_b32_e32 v3, s3
	v_ashrrev_i32_e32 v0, 2, v4
	v_and_or_b32 v2, v4, 31, s2
	s_lshl_b32 s2, s71, 1
	v_and_b32_e32 v5, 0xc0, v4
	v_and_b32_e32 v0, 0xffffffc0, v0
	s_add_u32 s2, s48, s2
	v_ashrrev_i32_e32 v1, 31, v0
	s_addc_u32 s3, s49, 0
	v_lshlrev_b32_e32 v128, 1, v5
	v_lshrrev_b32_e32 v4, 2, v4
	v_lshl_add_u64 v[0:1], v[2:3], 0, v[0:1]
	v_lshl_add_u64 v[2:3], s[2:3], 0, v[128:129]
	v_and_b32_e32 v128, 8, v4
	v_lshl_add_u64 v[2:3], v[2:3], 0, v[128:129]
	v_mad_u64_u32 v[2:3], s[2:3], v0, s15, v[2:3]
	v_cvt_f16_f32_e32 v0, v198
	v_cvt_f16_f32_e32 v4, v182
	v_mad_i32_i24 v3, v1, s15, v3
	v_cvt_pk_f16_f32 v1, v184, v185
	v_pack_b32_f16 v0, v0, v1
	v_alignbit_b32 v1, v4, v1, 16
	v_cvt_f16_f32_e32 v4, v183
	v_cvt_f16_f32_e32 v5, v178
	global_store_dwordx2 v[2:3], v[0:1], off
	v_cvt_pk_f16_f32 v1, v180, v181
	v_pack_b32_f16 v0, v4, v1
	v_alignbit_b32 v1, v5, v1, 16
	v_cvt_f16_f32_e32 v4, v179
	v_cvt_f16_f32_e32 v5, v174
	global_store_dwordx2 v[2:3], v[0:1], off offset:16
	v_cvt_pk_f16_f32 v1, v176, v177
	v_pack_b32_f16 v0, v4, v1
	v_alignbit_b32 v1, v5, v1, 16
	v_cvt_f16_f32_e32 v4, v175
	v_cvt_f16_f32_e32 v5, v196
	global_store_dwordx2 v[2:3], v[0:1], off offset:32
	v_cvt_pk_f16_f32 v1, v172, v173
	v_pack_b32_f16 v0, v4, v1
	v_alignbit_b32 v1, v5, v1, 16
	v_cvt_f16_f32_e32 v4, v195
	v_cvt_f16_f32_e32 v5, v168
	global_store_dwordx2 v[2:3], v[0:1], off offset:48
	v_cvt_pk_f16_f32 v1, v170, v171
	v_pack_b32_f16 v0, v4, v1
	v_alignbit_b32 v1, v5, v1, 16
	v_cvt_f16_f32_e32 v4, v169
	v_cvt_f16_f32_e32 v5, v164
	global_store_dwordx2 v[2:3], v[0:1], off offset:64
	v_cvt_pk_f16_f32 v1, v166, v167
	v_pack_b32_f16 v0, v4, v1
	v_alignbit_b32 v1, v5, v1, 16
	v_cvt_f16_f32_e32 v4, v165
	v_cvt_f16_f32_e32 v5, v160
	global_store_dwordx2 v[2:3], v[0:1], off offset:80
	v_cvt_pk_f16_f32 v1, v162, v163
	v_pack_b32_f16 v0, v4, v1
	v_alignbit_b32 v1, v5, v1, 16
	v_cvt_f16_f32_e32 v4, v161
	v_cvt_f16_f32_e32 v5, v194
	global_store_dwordx2 v[2:3], v[0:1], off offset:96
	v_cvt_pk_f16_f32 v1, v158, v159
	v_pack_b32_f16 v0, v4, v1
	v_alignbit_b32 v1, v5, v1, 16
	v_cvt_f16_f32_e32 v4, v193
	v_cvt_f16_f32_e32 v5, v154
	global_store_dwordx2 v[2:3], v[0:1], off offset:112
	v_cvt_pk_f16_f32 v1, v156, v157
	v_pack_b32_f16 v0, v4, v1
	v_alignbit_b32 v1, v5, v1, 16
	s_mov_b32 s2, 0x11000
	v_cvt_f16_f32_e32 v4, v155
	v_cvt_f16_f32_e32 v5, v150
	v_add_co_u32_e32 v2, vcc, s2, v2
	v_readlane_b32 s24, v255, 43
	s_nop 0
	v_addc_co_u32_e32 v3, vcc, 0, v3, vcc
	global_store_dwordx2 v[2:3], v[0:1], off
	v_cvt_pk_f16_f32 v1, v152, v153
	v_pack_b32_f16 v0, v4, v1
	v_alignbit_b32 v1, v5, v1, 16
	v_cvt_f16_f32_e32 v4, v151
	v_cvt_f16_f32_e32 v5, v146
	global_store_dwordx2 v[2:3], v[0:1], off offset:16
	v_cvt_pk_f16_f32 v1, v148, v149
	v_pack_b32_f16 v0, v4, v1
	v_alignbit_b32 v1, v5, v1, 16
	v_cvt_f16_f32_e32 v4, v147
	v_cvt_f16_f32_e32 v5, v192
	global_store_dwordx2 v[2:3], v[0:1], off offset:32
	v_cvt_pk_f16_f32 v1, v144, v145
	v_pack_b32_f16 v0, v4, v1
	v_alignbit_b32 v1, v5, v1, 16
	v_cvt_f16_f32_e32 v4, v191
	v_cvt_f16_f32_e32 v5, v140
	global_store_dwordx2 v[2:3], v[0:1], off offset:48
	v_cvt_pk_f16_f32 v1, v142, v143
	v_pack_b32_f16 v0, v4, v1
	v_alignbit_b32 v1, v5, v1, 16
	v_cvt_f16_f32_e32 v4, v141
	v_cvt_f16_f32_e32 v5, v136
	global_store_dwordx2 v[2:3], v[0:1], off offset:64
	v_cvt_pk_f16_f32 v1, v138, v139
	v_pack_b32_f16 v0, v4, v1
	v_alignbit_b32 v1, v5, v1, 16
	v_cvt_f16_f32_e32 v4, v137
	v_cvt_f16_f32_e32 v5, v132
	global_store_dwordx2 v[2:3], v[0:1], off offset:80
	v_cvt_pk_f16_f32 v1, v134, v135
	v_pack_b32_f16 v0, v4, v1
	v_alignbit_b32 v1, v5, v1, 16
	v_cvt_f16_f32_e32 v4, v133
	v_cvt_f16_f32_e32 v5, v190
	global_store_dwordx2 v[2:3], v[0:1], off offset:96
	v_cvt_pk_f16_f32 v1, v130, v131
	v_pack_b32_f16 v0, v4, v1
	v_alignbit_b32 v1, v5, v1, 16
	v_readlane_b32 s3, v255, 41
	v_readlane_b32 s25, v255, 47
	v_readlane_b32 s33, v255, 55
	v_mov_b32_e32 v215, 0x3c0881c4
	v_mov_b32_e32 v216, 0xbab64f3b
	global_store_dwordx2 v[2:3], v[0:1], off offset:112
	s_branch .LBB0_36
